# MFMA blocks of the GEMM K-loops reduced to barrier / 32 MFMA / barrier: redundant post-barrier lgkmcnt wait removed (on top of v46)
# speedup vs baseline: 1.0018x; 1.0018x over previous
.LBB0_577:
	ds_read_b128 v[128:131], v193
	ds_read_b128 v[132:135], v193 offset:1024
	ds_read_b128 v[136:139], v193 offset:2048
	ds_read_b128 v[140:143], v193 offset:3072
	ds_read_b128 v[144:147], v194
	ds_read_b128 v[148:151], v194 offset:1024
	ds_read_b128 v[152:155], v194 offset:2048
	ds_read_b128 v[156:159], v194 offset:3072
	s_add_u32 s35, s42, 0xfff80080
	s_addc_u32 s39, s43, -1
	s_cmp_eq_u32 s31, 4
	s_cselect_b32 s47, s1, s39
	s_cselect_b32 s46, s0, s35
	s_cselect_b32 s45, s37, s23
	s_cselect_b32 s44, s36, s11
	v_lshl_add_u64 v[218:219], s[42:43], 0, v[168:169]
	s_add_i32 m0, s7, 0xc000
	ds_read_b128 v[176:179], v195
	ds_read_b128 v[180:183], v195 offset:1024
	ds_read_b128 v[184:187], v195 offset:2048
	ds_read_b128 v[198:201], v195 offset:3072
	ds_read_b128 v[202:205], v195 offset:4096
	ds_read_b128 v[206:209], v195 offset:5120
	ds_read_b128 v[210:213], v195 offset:6144
	ds_read_b128 v[214:217], v195 offset:7168
	global_load_lds_dwordx4 v[218:219], off
	v_lshl_add_u64 v[218:219], s[42:43], 0, v[170:171]
	s_add_i32 m0, s7, 0xe000
	s_nop 0
	global_load_lds_dwordx4 v[218:219], off
	s_waitcnt vmcnt(8)
	s_waitcnt lgkmcnt(0)
	s_barrier
	v_mfma_f32_16x16x32_bf16 v[124:127], v[128:131], v[176:179], v[124:127]
	v_mfma_f32_16x16x32_bf16 v[120:123], v[136:139], v[176:179], v[120:123]
	v_mfma_f32_16x16x32_bf16 v[108:111], v[128:131], v[184:187], v[108:111]
	v_mfma_f32_16x16x32_bf16 v[104:107], v[136:139], v[184:187], v[104:107]
	v_mfma_f32_16x16x32_bf16 v[92:95], v[128:131], v[202:205], v[92:95]
	v_mfma_f32_16x16x32_bf16 v[88:91], v[136:139], v[202:205], v[88:91]
	v_mfma_f32_16x16x32_bf16 v[76:79], v[128:131], v[210:213], v[76:79]
	v_mfma_f32_16x16x32_bf16 v[72:75], v[136:139], v[210:213], v[72:75]
	v_mfma_f32_16x16x32_bf16 v[124:127], v[132:135], v[180:183], v[124:127]
	v_mfma_f32_16x16x32_bf16 v[120:123], v[140:143], v[180:183], v[120:123]
	v_mfma_f32_16x16x32_bf16 v[108:111], v[132:135], v[198:201], v[108:111]
	v_mfma_f32_16x16x32_bf16 v[104:107], v[140:143], v[198:201], v[104:107]
	v_mfma_f32_16x16x32_bf16 v[92:95], v[132:135], v[206:209], v[92:95]
	v_mfma_f32_16x16x32_bf16 v[88:91], v[140:143], v[206:209], v[88:91]
	v_mfma_f32_16x16x32_bf16 v[76:79], v[132:135], v[214:217], v[76:79]
	v_mfma_f32_16x16x32_bf16 v[72:75], v[140:143], v[214:217], v[72:75]
	v_mfma_f32_16x16x32_bf16 v[116:119], v[144:147], v[176:179], v[116:119]
	v_mfma_f32_16x16x32_bf16 v[112:115], v[152:155], v[176:179], v[112:115]
	v_mfma_f32_16x16x32_bf16 v[100:103], v[144:147], v[184:187], v[100:103]
	v_mfma_f32_16x16x32_bf16 v[96:99], v[152:155], v[184:187], v[96:99]
	v_mfma_f32_16x16x32_bf16 v[84:87], v[144:147], v[202:205], v[84:87]
	v_mfma_f32_16x16x32_bf16 v[80:83], v[152:155], v[202:205], v[80:83]
	v_mfma_f32_16x16x32_bf16 v[68:71], v[144:147], v[210:213], v[68:71]
	v_mfma_f32_16x16x32_bf16 v[64:67], v[152:155], v[210:213], v[64:67]
	v_mfma_f32_16x16x32_bf16 v[116:119], v[148:151], v[180:183], v[116:119]
	v_mfma_f32_16x16x32_bf16 v[112:115], v[156:159], v[180:183], v[112:115]
	v_mfma_f32_16x16x32_bf16 v[100:103], v[148:151], v[198:201], v[100:103]
	v_mfma_f32_16x16x32_bf16 v[96:99], v[156:159], v[198:201], v[96:99]
	v_mfma_f32_16x16x32_bf16 v[84:87], v[148:151], v[206:209], v[84:87]
	v_mfma_f32_16x16x32_bf16 v[80:83], v[156:159], v[206:209], v[80:83]
	v_mfma_f32_16x16x32_bf16 v[68:71], v[148:151], v[214:217], v[68:71]
	v_mfma_f32_16x16x32_bf16 v[64:67], v[156:159], v[214:217], v[64:67]
	s_barrier
	s_add_i32 s35, s48, s6
	v_lshl_add_u64 v[218:219], s[44:45], 0, v[162:163]
	s_mov_b32 m0, s35
	ds_read_b128 v[176:179], v195 offset:16384
	ds_read_b128 v[180:183], v195 offset:17408
	ds_read_b128 v[184:187], v195 offset:18432
	ds_read_b128 v[198:201], v195 offset:19456
	ds_read_b128 v[202:205], v195 offset:20480
	ds_read_b128 v[206:209], v195 offset:21504
	ds_read_b128 v[210:213], v195 offset:22528
	ds_read_b128 v[214:217], v195 offset:23552
	global_load_lds_dwordx4 v[218:219], off
	s_add_i32 m0, s35, 0x2000
	s_add_u32 s50, s44, 0x20000
	v_lshl_add_u64 v[220:221], s[44:45], 0, v[166:167]
	s_addc_u32 s51, s45, 0
	s_add_i32 s35, s49, s6
	global_load_lds_dwordx4 v[220:221], off
	v_lshl_add_u64 v[222:223], s[50:51], 0, v[162:163]
	s_mov_b32 m0, s35
	v_lshl_add_u64 v[224:225], s[46:47], 0, v[164:165]
	global_load_lds_dwordx4 v[222:223], off
	v_lshl_add_u64 v[222:223], s[50:51], 0, v[166:167]
	s_add_i32 m0, s35, 0x2000
	s_nop 0
	global_load_lds_dwordx4 v[222:223], off
	v_lshl_add_u64 v[222:223], s[46:47], 0, v[160:161]
	s_mov_b32 m0, s7
	s_nop 0
	global_load_lds_dwordx4 v[222:223], off
	s_mov_b32 m0, s8
	s_nop 0
	global_load_lds_dwordx4 v[224:225], off
	s_waitcnt vmcnt(8)
	s_waitcnt lgkmcnt(0)
	s_barrier
	v_mfma_f32_16x16x32_bf16 v[60:63], v[128:131], v[176:179], v[60:63]
	v_mfma_f32_16x16x32_bf16 v[56:59], v[136:139], v[176:179], v[56:59]
	v_mfma_f32_16x16x32_bf16 v[44:47], v[128:131], v[184:187], v[44:47]
	v_mfma_f32_16x16x32_bf16 v[40:43], v[136:139], v[184:187], v[40:43]
	v_mfma_f32_16x16x32_bf16 v[28:31], v[128:131], v[202:205], v[28:31]
	v_mfma_f32_16x16x32_bf16 v[24:27], v[136:139], v[202:205], v[24:27]
	v_mfma_f32_16x16x32_bf16 v[12:15], v[128:131], v[210:213], v[12:15]
	v_mfma_f32_16x16x32_bf16 v[8:11], v[136:139], v[210:213], v[8:11]
	v_mfma_f32_16x16x32_bf16 v[60:63], v[132:135], v[180:183], v[60:63]
	v_mfma_f32_16x16x32_bf16 v[56:59], v[140:143], v[180:183], v[56:59]
	v_mfma_f32_16x16x32_bf16 v[44:47], v[132:135], v[198:201], v[44:47]
	v_mfma_f32_16x16x32_bf16 v[40:43], v[140:143], v[198:201], v[40:43]
	v_mfma_f32_16x16x32_bf16 v[28:31], v[132:135], v[206:209], v[28:31]
	v_mfma_f32_16x16x32_bf16 v[24:27], v[140:143], v[206:209], v[24:27]
	v_mfma_f32_16x16x32_bf16 v[12:15], v[132:135], v[214:217], v[12:15]
	v_mfma_f32_16x16x32_bf16 v[8:11], v[140:143], v[214:217], v[8:11]
	v_mfma_f32_16x16x32_bf16 v[52:55], v[144:147], v[176:179], v[52:55]
	v_mfma_f32_16x16x32_bf16 v[48:51], v[152:155], v[176:179], v[48:51]
	v_mfma_f32_16x16x32_bf16 v[36:39], v[144:147], v[184:187], v[36:39]
	v_mfma_f32_16x16x32_bf16 v[32:35], v[152:155], v[184:187], v[32:35]
	v_mfma_f32_16x16x32_bf16 v[20:23], v[144:147], v[202:205], v[20:23]
	v_mfma_f32_16x16x32_bf16 v[16:19], v[152:155], v[202:205], v[16:19]
	v_mfma_f32_16x16x32_bf16 v[4:7], v[144:147], v[210:213], v[4:7]
	v_mfma_f32_16x16x32_bf16 v[0:3], v[152:155], v[210:213], v[0:3]
	v_mfma_f32_16x16x32_bf16 v[52:55], v[148:151], v[180:183], v[52:55]
	v_mfma_f32_16x16x32_bf16 v[48:51], v[156:159], v[180:183], v[48:51]
	v_mfma_f32_16x16x32_bf16 v[36:39], v[148:151], v[198:201], v[36:39]
	v_mfma_f32_16x16x32_bf16 v[32:35], v[156:159], v[198:201], v[32:35]
	v_mfma_f32_16x16x32_bf16 v[20:23], v[148:151], v[206:209], v[20:23]
	v_mfma_f32_16x16x32_bf16 v[16:19], v[156:159], v[206:209], v[16:19]
	v_mfma_f32_16x16x32_bf16 v[4:7], v[148:151], v[214:217], v[4:7]
	v_mfma_f32_16x16x32_bf16 v[0:3], v[156:159], v[214:217], v[0:3]
	s_barrier
	s_add_i32 s35, 0, 0x18000
	s_add_i32 s39, 0, 0x1c000
	v_add_u32_e32 v140, s35, v191
	v_add_u32_e32 v156, s39, v191
	ds_read_b128 v[128:131], v140
	ds_read_b128 v[132:135], v140 offset:1024
	ds_read_b128 v[136:139], v140 offset:2048
	ds_read_b128 v[140:143], v140 offset:3072
	ds_read_b128 v[144:147], v156
	ds_read_b128 v[148:151], v156 offset:1024
	ds_read_b128 v[152:155], v156 offset:2048
	ds_read_b128 v[156:159], v156 offset:3072
	s_add_u32 s46, s46, 0x80000
	s_addc_u32 s47, s47, 0
	s_mov_b32 m0, s9
	v_lshl_add_u64 v[226:227], s[46:47], 0, v[160:161]
	ds_read_b128 v[176:179], v195 offset:32768
	ds_read_b128 v[180:183], v195 offset:33792
	ds_read_b128 v[184:187], v195 offset:34816
	ds_read_b128 v[198:201], v195 offset:35840
	ds_read_b128 v[202:205], v195 offset:36864
	ds_read_b128 v[206:209], v195 offset:37888
	ds_read_b128 v[210:213], v195 offset:38912
	ds_read_b128 v[214:217], v195 offset:39936
	global_load_lds_dwordx4 v[226:227], off
	v_lshl_add_u64 v[226:227], s[46:47], 0, v[164:165]
	s_mov_b32 m0, s24
	s_nop 0
	global_load_lds_dwordx4 v[226:227], off
	s_waitcnt vmcnt(8)
	s_waitcnt lgkmcnt(0)
	s_barrier
	v_mfma_f32_16x16x32_bf16 v[124:127], v[128:131], v[176:179], v[124:127]
	v_mfma_f32_16x16x32_bf16 v[120:123], v[136:139], v[176:179], v[120:123]
	v_mfma_f32_16x16x32_bf16 v[108:111], v[128:131], v[184:187], v[108:111]
	v_mfma_f32_16x16x32_bf16 v[104:107], v[136:139], v[184:187], v[104:107]
	v_mfma_f32_16x16x32_bf16 v[92:95], v[128:131], v[202:205], v[92:95]
	v_mfma_f32_16x16x32_bf16 v[88:91], v[136:139], v[202:205], v[88:91]
	v_mfma_f32_16x16x32_bf16 v[76:79], v[128:131], v[210:213], v[76:79]
	v_mfma_f32_16x16x32_bf16 v[72:75], v[136:139], v[210:213], v[72:75]
	v_mfma_f32_16x16x32_bf16 v[124:127], v[132:135], v[180:183], v[124:127]
	v_mfma_f32_16x16x32_bf16 v[120:123], v[140:143], v[180:183], v[120:123]
	v_mfma_f32_16x16x32_bf16 v[108:111], v[132:135], v[198:201], v[108:111]
	v_mfma_f32_16x16x32_bf16 v[104:107], v[140:143], v[198:201], v[104:107]
	v_mfma_f32_16x16x32_bf16 v[92:95], v[132:135], v[206:209], v[92:95]
	v_mfma_f32_16x16x32_bf16 v[88:91], v[140:143], v[206:209], v[88:91]
	v_mfma_f32_16x16x32_bf16 v[76:79], v[132:135], v[214:217], v[76:79]
	v_mfma_f32_16x16x32_bf16 v[72:75], v[140:143], v[214:217], v[72:75]
	v_mfma_f32_16x16x32_bf16 v[116:119], v[144:147], v[176:179], v[116:119]
	v_mfma_f32_16x16x32_bf16 v[112:115], v[152:155], v[176:179], v[112:115]
	v_mfma_f32_16x16x32_bf16 v[100:103], v[144:147], v[184:187], v[100:103]
	v_mfma_f32_16x16x32_bf16 v[96:99], v[152:155], v[184:187], v[96:99]
	v_mfma_f32_16x16x32_bf16 v[84:87], v[144:147], v[202:205], v[84:87]
	v_mfma_f32_16x16x32_bf16 v[80:83], v[152:155], v[202:205], v[80:83]
	v_mfma_f32_16x16x32_bf16 v[68:71], v[144:147], v[210:213], v[68:71]
	v_mfma_f32_16x16x32_bf16 v[64:67], v[152:155], v[210:213], v[64:67]
	v_mfma_f32_16x16x32_bf16 v[116:119], v[148:151], v[180:183], v[116:119]
	v_mfma_f32_16x16x32_bf16 v[112:115], v[156:159], v[180:183], v[112:115]
	v_mfma_f32_16x16x32_bf16 v[100:103], v[148:151], v[198:201], v[100:103]
	v_mfma_f32_16x16x32_bf16 v[96:99], v[156:159], v[198:201], v[96:99]
	v_mfma_f32_16x16x32_bf16 v[84:87], v[148:151], v[206:209], v[84:87]
	v_mfma_f32_16x16x32_bf16 v[80:83], v[156:159], v[206:209], v[80:83]
	v_mfma_f32_16x16x32_bf16 v[68:71], v[148:151], v[214:217], v[68:71]
	v_mfma_f32_16x16x32_bf16 v[64:67], v[156:159], v[214:217], v[64:67]
	s_barrier
	s_add_i32 s35, s35, s6
	v_lshl_add_u64 v[218:219], v[218:219], 0, s[16:17]
	s_mov_b32 m0, s35
	ds_read_b128 v[176:179], v195 offset:49152
	ds_read_b128 v[180:183], v195 offset:50176
	ds_read_b128 v[184:187], v195 offset:51200
	ds_read_b128 v[198:201], v195 offset:52224
	ds_read_b128 v[202:205], v195 offset:53248
	ds_read_b128 v[206:209], v195 offset:54272
	ds_read_b128 v[210:213], v195 offset:55296
	ds_read_b128 v[214:217], v195 offset:56320
	global_load_lds_dwordx4 v[218:219], off
	s_add_i32 m0, s35, 0x2000
	s_add_u32 s44, s44, 0x20080
	v_lshl_add_u64 v[218:219], v[220:221], 0, s[16:17]
	s_addc_u32 s45, s45, 0
	s_add_i32 s35, s39, s6
	global_load_lds_dwordx4 v[218:219], off
	v_lshl_add_u64 v[218:219], s[44:45], 0, v[162:163]
	s_mov_b32 m0, s35
	s_nop 0
	global_load_lds_dwordx4 v[218:219], off
	v_lshl_add_u64 v[218:219], s[44:45], 0, v[166:167]
	s_add_i32 m0, s35, 0x2000
	s_nop 0
	global_load_lds_dwordx4 v[218:219], off
	v_lshl_add_u64 v[218:219], v[222:223], 0, s[16:17]
	s_mov_b32 m0, s28
	s_nop 0
	global_load_lds_dwordx4 v[218:219], off
	v_lshl_add_u64 v[218:219], v[224:225], 0, s[16:17]
	s_mov_b32 m0, s29
	s_nop 0
	global_load_lds_dwordx4 v[218:219], off
	s_waitcnt vmcnt(8)
	s_waitcnt lgkmcnt(0)
	s_barrier
	v_mfma_f32_16x16x32_bf16 v[60:63], v[128:131], v[176:179], v[60:63]
	v_mfma_f32_16x16x32_bf16 v[56:59], v[136:139], v[176:179], v[56:59]
	v_mfma_f32_16x16x32_bf16 v[44:47], v[128:131], v[184:187], v[44:47]
	v_mfma_f32_16x16x32_bf16 v[40:43], v[136:139], v[184:187], v[40:43]
	v_mfma_f32_16x16x32_bf16 v[28:31], v[128:131], v[202:205], v[28:31]
	v_mfma_f32_16x16x32_bf16 v[24:27], v[136:139], v[202:205], v[24:27]
	v_mfma_f32_16x16x32_bf16 v[12:15], v[128:131], v[210:213], v[12:15]
	v_mfma_f32_16x16x32_bf16 v[8:11], v[136:139], v[210:213], v[8:11]
	v_mfma_f32_16x16x32_bf16 v[60:63], v[132:135], v[180:183], v[60:63]
	v_mfma_f32_16x16x32_bf16 v[56:59], v[140:143], v[180:183], v[56:59]
	v_mfma_f32_16x16x32_bf16 v[44:47], v[132:135], v[198:201], v[44:47]
	v_mfma_f32_16x16x32_bf16 v[40:43], v[140:143], v[198:201], v[40:43]
	v_mfma_f32_16x16x32_bf16 v[28:31], v[132:135], v[206:209], v[28:31]
	v_mfma_f32_16x16x32_bf16 v[24:27], v[140:143], v[206:209], v[24:27]
	v_mfma_f32_16x16x32_bf16 v[12:15], v[132:135], v[214:217], v[12:15]
	v_mfma_f32_16x16x32_bf16 v[8:11], v[140:143], v[214:217], v[8:11]
	v_mfma_f32_16x16x32_bf16 v[52:55], v[144:147], v[176:179], v[52:55]
	v_mfma_f32_16x16x32_bf16 v[48:51], v[152:155], v[176:179], v[48:51]
	v_mfma_f32_16x16x32_bf16 v[36:39], v[144:147], v[184:187], v[36:39]
	v_mfma_f32_16x16x32_bf16 v[32:35], v[152:155], v[184:187], v[32:35]
	v_mfma_f32_16x16x32_bf16 v[20:23], v[144:147], v[202:205], v[20:23]
	v_mfma_f32_16x16x32_bf16 v[16:19], v[152:155], v[202:205], v[16:19]
	v_mfma_f32_16x16x32_bf16 v[4:7], v[144:147], v[210:213], v[4:7]
	v_mfma_f32_16x16x32_bf16 v[0:3], v[152:155], v[210:213], v[0:3]
	v_mfma_f32_16x16x32_bf16 v[52:55], v[148:151], v[180:183], v[52:55]
	v_mfma_f32_16x16x32_bf16 v[48:51], v[156:159], v[180:183], v[48:51]
	v_mfma_f32_16x16x32_bf16 v[36:39], v[148:151], v[198:201], v[36:39]
	v_mfma_f32_16x16x32_bf16 v[32:35], v[156:159], v[198:201], v[32:35]
	v_mfma_f32_16x16x32_bf16 v[20:23], v[148:151], v[206:209], v[20:23]
	v_mfma_f32_16x16x32_bf16 v[16:19], v[156:159], v[206:209], v[16:19]
	v_mfma_f32_16x16x32_bf16 v[4:7], v[148:151], v[214:217], v[4:7]
	v_mfma_f32_16x16x32_bf16 v[0:3], v[156:159], v[214:217], v[0:3]
	s_barrier
	s_add_i32 s31, s31, 2
	s_add_u32 s42, s42, 0x100
	s_addc_u32 s43, s43, 0
	s_add_u32 s11, s11, 0x100
	s_addc_u32 s23, s23, 0
	s_cmp_gt_u32 s31, 5
	s_cbranch_scc0 .LBB0_577
	s_and_b64 vcc, exec, s[18:19]
	s_cbranch_vccz .LBB0_580
	s_barrier

.LBB0_664:
	ds_read_b128 v[156:159], v151
	ds_read_b128 v[160:163], v151 offset:1024
	ds_read_b128 v[164:167], v151 offset:2048
	ds_read_b128 v[168:171], v151 offset:3072
	ds_read_b128 v[172:175], v152
	ds_read_b128 v[176:179], v152 offset:1024
	ds_read_b128 v[180:183], v152 offset:2048
	ds_read_b128 v[184:187], v152 offset:3072
	s_add_u32 s22, s20, 0xfff80080
	s_addc_u32 s23, s21, -1
	s_cmp_eq_u32 s48, 28
	s_cselect_b32 s31, s13, s23
	s_cselect_b32 s30, s44, s22
	s_cselect_b32 s23, s15, s47
	s_cselect_b32 s22, s45, s46
	v_lshl_add_u64 v[146:147], s[20:21], 0, v[138:139]
	s_add_i32 m0, s11, 0xc000
	ds_read_b128 v[190:193], v153
	ds_read_b128 v[194:197], v153 offset:1024
	ds_read_b128 v[198:201], v153 offset:2048
	ds_read_b128 v[202:205], v153 offset:3072
	ds_read_b128 v[206:209], v153 offset:4096
	ds_read_b128 v[210:213], v153 offset:5120
	ds_read_b128 v[214:217], v153 offset:6144
	ds_read_b128 v[218:221], v153 offset:7168
	global_load_lds_dwordx4 v[146:147], off
	v_lshl_add_u64 v[146:147], s[20:21], 0, v[140:141]
	s_add_i32 m0, s11, 0xe000
	s_nop 0
	global_load_lds_dwordx4 v[146:147], off
	s_waitcnt vmcnt(8)
	s_waitcnt lgkmcnt(0)
	s_barrier
	v_mfma_f32_16x16x32_bf16 v[116:119], v[156:159], v[190:193], v[116:119]
	v_mfma_f32_16x16x32_bf16 v[112:115], v[164:167], v[190:193], v[112:115]
	v_mfma_f32_16x16x32_bf16 v[100:103], v[156:159], v[198:201], v[100:103]
	v_mfma_f32_16x16x32_bf16 v[96:99], v[164:167], v[198:201], v[96:99]
	v_mfma_f32_16x16x32_bf16 v[84:87], v[156:159], v[206:209], v[84:87]
	v_mfma_f32_16x16x32_bf16 v[80:83], v[164:167], v[206:209], v[80:83]
	v_mfma_f32_16x16x32_bf16 v[68:71], v[156:159], v[214:217], v[68:71]
	v_mfma_f32_16x16x32_bf16 v[64:67], v[164:167], v[214:217], v[64:67]
	v_mfma_f32_16x16x32_bf16 v[116:119], v[160:163], v[194:197], v[116:119]
	v_mfma_f32_16x16x32_bf16 v[112:115], v[168:171], v[194:197], v[112:115]
	v_mfma_f32_16x16x32_bf16 v[100:103], v[160:163], v[202:205], v[100:103]
	v_mfma_f32_16x16x32_bf16 v[96:99], v[168:171], v[202:205], v[96:99]
	v_mfma_f32_16x16x32_bf16 v[84:87], v[160:163], v[210:213], v[84:87]
	v_mfma_f32_16x16x32_bf16 v[80:83], v[168:171], v[210:213], v[80:83]
	v_mfma_f32_16x16x32_bf16 v[68:71], v[160:163], v[218:221], v[68:71]
	v_mfma_f32_16x16x32_bf16 v[64:67], v[168:171], v[218:221], v[64:67]
	v_mfma_f32_16x16x32_bf16 v[124:127], v[172:175], v[190:193], v[124:127]
	v_mfma_f32_16x16x32_bf16 v[120:123], v[180:183], v[190:193], v[120:123]
	v_mfma_f32_16x16x32_bf16 v[108:111], v[172:175], v[198:201], v[108:111]
	v_mfma_f32_16x16x32_bf16 v[104:107], v[180:183], v[198:201], v[104:107]
	v_mfma_f32_16x16x32_bf16 v[92:95], v[172:175], v[206:209], v[92:95]
	v_mfma_f32_16x16x32_bf16 v[88:91], v[180:183], v[206:209], v[88:91]
	v_mfma_f32_16x16x32_bf16 v[76:79], v[172:175], v[214:217], v[76:79]
	v_mfma_f32_16x16x32_bf16 v[72:75], v[180:183], v[214:217], v[72:75]
	v_mfma_f32_16x16x32_bf16 v[124:127], v[176:179], v[194:197], v[124:127]
	v_mfma_f32_16x16x32_bf16 v[120:123], v[184:187], v[194:197], v[120:123]
	v_mfma_f32_16x16x32_bf16 v[108:111], v[176:179], v[202:205], v[108:111]
	v_mfma_f32_16x16x32_bf16 v[104:107], v[184:187], v[202:205], v[104:107]
	v_mfma_f32_16x16x32_bf16 v[92:95], v[176:179], v[210:213], v[92:95]
	v_mfma_f32_16x16x32_bf16 v[88:91], v[184:187], v[210:213], v[88:91]
	v_mfma_f32_16x16x32_bf16 v[76:79], v[176:179], v[218:221], v[76:79]
	v_mfma_f32_16x16x32_bf16 v[72:75], v[184:187], v[218:221], v[72:75]
	s_barrier
	s_add_i32 s49, s40, s26
	v_lshl_add_u64 v[146:147], s[22:23], 0, v[130:131]
	s_mov_b32 m0, s49
	ds_read_b128 v[190:193], v153 offset:16384
	ds_read_b128 v[194:197], v153 offset:17408
	ds_read_b128 v[198:201], v153 offset:18432
	ds_read_b128 v[202:205], v153 offset:19456
	ds_read_b128 v[206:209], v153 offset:20480
	ds_read_b128 v[210:213], v153 offset:21504
	ds_read_b128 v[214:217], v153 offset:22528
	ds_read_b128 v[218:221], v153 offset:23552
	global_load_lds_dwordx4 v[146:147], off
	s_add_i32 m0, s49, 0x2000
	s_add_u32 s50, s22, 0x80000
	v_lshl_add_u64 v[222:223], s[22:23], 0, v[134:135]
	s_addc_u32 s51, s23, 0
	s_add_i32 s49, s41, s26
	global_load_lds_dwordx4 v[222:223], off
	v_lshl_add_u64 v[224:225], s[50:51], 0, v[130:131]
	s_mov_b32 m0, s49
	v_lshl_add_u64 v[226:227], s[30:31], 0, v[132:133]
	global_load_lds_dwordx4 v[224:225], off
	v_lshl_add_u64 v[224:225], s[50:51], 0, v[134:135]
	s_add_i32 m0, s49, 0x2000
	s_nop 0
	global_load_lds_dwordx4 v[224:225], off
	v_lshl_add_u64 v[224:225], s[30:31], 0, v[128:129]
	s_mov_b32 m0, s11
	s_nop 0
	global_load_lds_dwordx4 v[224:225], off
	s_mov_b32 m0, s28
	s_nop 0
	global_load_lds_dwordx4 v[226:227], off
	s_waitcnt vmcnt(8)
	s_waitcnt lgkmcnt(0)
	s_barrier
	v_mfma_f32_16x16x32_bf16 v[52:55], v[156:159], v[190:193], v[52:55]
	v_mfma_f32_16x16x32_bf16 v[48:51], v[164:167], v[190:193], v[48:51]
	v_mfma_f32_16x16x32_bf16 v[36:39], v[156:159], v[198:201], v[36:39]
	v_mfma_f32_16x16x32_bf16 v[32:35], v[164:167], v[198:201], v[32:35]
	v_mfma_f32_16x16x32_bf16 v[20:23], v[156:159], v[206:209], v[20:23]
	v_mfma_f32_16x16x32_bf16 v[16:19], v[164:167], v[206:209], v[16:19]
	v_mfma_f32_16x16x32_bf16 v[8:11], v[156:159], v[214:217], v[8:11]
	v_mfma_f32_16x16x32_bf16 v[0:3], v[164:167], v[214:217], v[0:3]
	v_mfma_f32_16x16x32_bf16 v[52:55], v[160:163], v[194:197], v[52:55]
	v_mfma_f32_16x16x32_bf16 v[48:51], v[168:171], v[194:197], v[48:51]
	v_mfma_f32_16x16x32_bf16 v[36:39], v[160:163], v[202:205], v[36:39]
	v_mfma_f32_16x16x32_bf16 v[32:35], v[168:171], v[202:205], v[32:35]
	v_mfma_f32_16x16x32_bf16 v[20:23], v[160:163], v[210:213], v[20:23]
	v_mfma_f32_16x16x32_bf16 v[16:19], v[168:171], v[210:213], v[16:19]
	v_mfma_f32_16x16x32_bf16 v[8:11], v[160:163], v[218:221], v[8:11]
	v_mfma_f32_16x16x32_bf16 v[0:3], v[168:171], v[218:221], v[0:3]
	v_mfma_f32_16x16x32_bf16 v[60:63], v[172:175], v[190:193], v[60:63]
	v_mfma_f32_16x16x32_bf16 v[56:59], v[180:183], v[190:193], v[56:59]
	v_mfma_f32_16x16x32_bf16 v[44:47], v[172:175], v[198:201], v[44:47]
	v_mfma_f32_16x16x32_bf16 v[40:43], v[180:183], v[198:201], v[40:43]
	v_mfma_f32_16x16x32_bf16 v[28:31], v[172:175], v[206:209], v[28:31]
	v_mfma_f32_16x16x32_bf16 v[24:27], v[180:183], v[206:209], v[24:27]
	v_mfma_f32_16x16x32_bf16 v[12:15], v[172:175], v[214:217], v[12:15]
	v_mfma_f32_16x16x32_bf16 v[4:7], v[180:183], v[214:217], v[4:7]
	v_mfma_f32_16x16x32_bf16 v[60:63], v[176:179], v[194:197], v[60:63]
	v_mfma_f32_16x16x32_bf16 v[56:59], v[184:187], v[194:197], v[56:59]
	v_mfma_f32_16x16x32_bf16 v[44:47], v[176:179], v[202:205], v[44:47]
	v_mfma_f32_16x16x32_bf16 v[40:43], v[184:187], v[202:205], v[40:43]
	v_mfma_f32_16x16x32_bf16 v[28:31], v[176:179], v[210:213], v[28:31]
	v_mfma_f32_16x16x32_bf16 v[24:27], v[184:187], v[210:213], v[24:27]
	v_mfma_f32_16x16x32_bf16 v[12:15], v[176:179], v[218:221], v[12:15]
	v_mfma_f32_16x16x32_bf16 v[4:7], v[184:187], v[218:221], v[4:7]
	s_barrier
	s_add_i32 s49, 0, 0x18000
	s_add_i32 s50, 0, 0x1c000
	v_add_u32_e32 v168, s49, v149
	v_add_u32_e32 v184, s50, v149
	ds_read_b128 v[156:159], v168
	ds_read_b128 v[160:163], v168 offset:1024
	ds_read_b128 v[164:167], v168 offset:2048
	ds_read_b128 v[168:171], v168 offset:3072
	ds_read_b128 v[172:175], v184
	ds_read_b128 v[176:179], v184 offset:1024
	ds_read_b128 v[180:183], v184 offset:2048
	ds_read_b128 v[184:187], v184 offset:3072
	s_add_u32 s30, s30, 0x80000
	s_addc_u32 s31, s31, 0
	s_mov_b32 m0, s29
	v_lshl_add_u64 v[228:229], s[30:31], 0, v[128:129]
	ds_read_b128 v[190:193], v153 offset:32768
	ds_read_b128 v[194:197], v153 offset:33792
	ds_read_b128 v[198:201], v153 offset:34816
	ds_read_b128 v[202:205], v153 offset:35840
	ds_read_b128 v[206:209], v153 offset:36864
	ds_read_b128 v[210:213], v153 offset:37888
	ds_read_b128 v[214:217], v153 offset:38912
	ds_read_b128 v[218:221], v153 offset:39936
	global_load_lds_dwordx4 v[228:229], off
	v_lshl_add_u64 v[228:229], s[30:31], 0, v[132:133]
	s_mov_b32 m0, s33
	s_nop 0
	global_load_lds_dwordx4 v[228:229], off
	s_waitcnt vmcnt(8)
	s_waitcnt lgkmcnt(0)
	s_barrier
	v_mfma_f32_16x16x32_bf16 v[116:119], v[156:159], v[190:193], v[116:119]
	v_mfma_f32_16x16x32_bf16 v[112:115], v[164:167], v[190:193], v[112:115]
	v_mfma_f32_16x16x32_bf16 v[100:103], v[156:159], v[198:201], v[100:103]
	v_mfma_f32_16x16x32_bf16 v[96:99], v[164:167], v[198:201], v[96:99]
	v_mfma_f32_16x16x32_bf16 v[84:87], v[156:159], v[206:209], v[84:87]
	v_mfma_f32_16x16x32_bf16 v[80:83], v[164:167], v[206:209], v[80:83]
	v_mfma_f32_16x16x32_bf16 v[68:71], v[156:159], v[214:217], v[68:71]
	v_mfma_f32_16x16x32_bf16 v[64:67], v[164:167], v[214:217], v[64:67]
	v_mfma_f32_16x16x32_bf16 v[116:119], v[160:163], v[194:197], v[116:119]
	v_mfma_f32_16x16x32_bf16 v[112:115], v[168:171], v[194:197], v[112:115]
	v_mfma_f32_16x16x32_bf16 v[100:103], v[160:163], v[202:205], v[100:103]
	v_mfma_f32_16x16x32_bf16 v[96:99], v[168:171], v[202:205], v[96:99]
	v_mfma_f32_16x16x32_bf16 v[84:87], v[160:163], v[210:213], v[84:87]
	v_mfma_f32_16x16x32_bf16 v[80:83], v[168:171], v[210:213], v[80:83]
	v_mfma_f32_16x16x32_bf16 v[68:71], v[160:163], v[218:221], v[68:71]
	v_mfma_f32_16x16x32_bf16 v[64:67], v[168:171], v[218:221], v[64:67]
	v_mfma_f32_16x16x32_bf16 v[124:127], v[172:175], v[190:193], v[124:127]
	v_mfma_f32_16x16x32_bf16 v[120:123], v[180:183], v[190:193], v[120:123]
	v_mfma_f32_16x16x32_bf16 v[108:111], v[172:175], v[198:201], v[108:111]
	v_mfma_f32_16x16x32_bf16 v[104:107], v[180:183], v[198:201], v[104:107]
	v_mfma_f32_16x16x32_bf16 v[92:95], v[172:175], v[206:209], v[92:95]
	v_mfma_f32_16x16x32_bf16 v[88:91], v[180:183], v[206:209], v[88:91]
	v_mfma_f32_16x16x32_bf16 v[76:79], v[172:175], v[214:217], v[76:79]
	v_mfma_f32_16x16x32_bf16 v[72:75], v[180:183], v[214:217], v[72:75]
	v_mfma_f32_16x16x32_bf16 v[124:127], v[176:179], v[194:197], v[124:127]
	v_mfma_f32_16x16x32_bf16 v[120:123], v[184:187], v[194:197], v[120:123]
	v_mfma_f32_16x16x32_bf16 v[108:111], v[176:179], v[202:205], v[108:111]
	v_mfma_f32_16x16x32_bf16 v[104:107], v[184:187], v[202:205], v[104:107]
	v_mfma_f32_16x16x32_bf16 v[92:95], v[176:179], v[210:213], v[92:95]
	v_mfma_f32_16x16x32_bf16 v[88:91], v[184:187], v[210:213], v[88:91]
	v_mfma_f32_16x16x32_bf16 v[76:79], v[176:179], v[218:221], v[76:79]
	v_mfma_f32_16x16x32_bf16 v[72:75], v[184:187], v[218:221], v[72:75]
	s_barrier
	s_add_i32 s30, s49, s26
	v_lshl_add_u64 v[146:147], v[146:147], 0, s[6:7]
	s_mov_b32 m0, s30
	ds_read_b128 v[190:193], v153 offset:49152
	ds_read_b128 v[194:197], v153 offset:50176
	ds_read_b128 v[198:201], v153 offset:51200
	ds_read_b128 v[202:205], v153 offset:52224
	ds_read_b128 v[206:209], v153 offset:53248
	ds_read_b128 v[210:213], v153 offset:54272
	ds_read_b128 v[214:217], v153 offset:55296
	ds_read_b128 v[218:221], v153 offset:56320
	global_load_lds_dwordx4 v[146:147], off
	s_add_i32 m0, s30, 0x2000
	s_add_u32 s22, s22, 0x80080
	v_lshl_add_u64 v[146:147], v[222:223], 0, s[6:7]
	s_addc_u32 s23, s23, 0
	s_add_i32 s30, s50, s26
	global_load_lds_dwordx4 v[146:147], off
	v_lshl_add_u64 v[146:147], s[22:23], 0, v[130:131]
	s_mov_b32 m0, s30
	s_nop 0
	global_load_lds_dwordx4 v[146:147], off
	v_lshl_add_u64 v[146:147], s[22:23], 0, v[134:135]
	s_add_i32 m0, s30, 0x2000
	s_nop 0
	global_load_lds_dwordx4 v[146:147], off
	v_lshl_add_u64 v[146:147], v[224:225], 0, s[6:7]
	s_mov_b32 m0, s37
	s_nop 0
	global_load_lds_dwordx4 v[146:147], off
	v_lshl_add_u64 v[146:147], v[226:227], 0, s[6:7]
	s_mov_b32 m0, s38
	s_nop 0
	global_load_lds_dwordx4 v[146:147], off
	s_waitcnt vmcnt(8)
	s_waitcnt lgkmcnt(0)
	s_barrier
	v_mfma_f32_16x16x32_bf16 v[52:55], v[156:159], v[190:193], v[52:55]
	v_mfma_f32_16x16x32_bf16 v[48:51], v[164:167], v[190:193], v[48:51]
	v_mfma_f32_16x16x32_bf16 v[36:39], v[156:159], v[198:201], v[36:39]
	v_mfma_f32_16x16x32_bf16 v[32:35], v[164:167], v[198:201], v[32:35]
	v_mfma_f32_16x16x32_bf16 v[20:23], v[156:159], v[206:209], v[20:23]
	v_mfma_f32_16x16x32_bf16 v[16:19], v[164:167], v[206:209], v[16:19]
	v_mfma_f32_16x16x32_bf16 v[8:11], v[156:159], v[214:217], v[8:11]
	v_mfma_f32_16x16x32_bf16 v[0:3], v[164:167], v[214:217], v[0:3]
	v_mfma_f32_16x16x32_bf16 v[52:55], v[160:163], v[194:197], v[52:55]
	v_mfma_f32_16x16x32_bf16 v[48:51], v[168:171], v[194:197], v[48:51]
	v_mfma_f32_16x16x32_bf16 v[36:39], v[160:163], v[202:205], v[36:39]
	v_mfma_f32_16x16x32_bf16 v[32:35], v[168:171], v[202:205], v[32:35]
	v_mfma_f32_16x16x32_bf16 v[20:23], v[160:163], v[210:213], v[20:23]
	v_mfma_f32_16x16x32_bf16 v[16:19], v[168:171], v[210:213], v[16:19]
	v_mfma_f32_16x16x32_bf16 v[8:11], v[160:163], v[218:221], v[8:11]
	v_mfma_f32_16x16x32_bf16 v[0:3], v[168:171], v[218:221], v[0:3]
	v_mfma_f32_16x16x32_bf16 v[60:63], v[172:175], v[190:193], v[60:63]
	v_mfma_f32_16x16x32_bf16 v[56:59], v[180:183], v[190:193], v[56:59]
	v_mfma_f32_16x16x32_bf16 v[44:47], v[172:175], v[198:201], v[44:47]
	v_mfma_f32_16x16x32_bf16 v[40:43], v[180:183], v[198:201], v[40:43]
	v_mfma_f32_16x16x32_bf16 v[28:31], v[172:175], v[206:209], v[28:31]
	v_mfma_f32_16x16x32_bf16 v[24:27], v[180:183], v[206:209], v[24:27]
	v_mfma_f32_16x16x32_bf16 v[12:15], v[172:175], v[214:217], v[12:15]
	v_mfma_f32_16x16x32_bf16 v[4:7], v[180:183], v[214:217], v[4:7]
	v_mfma_f32_16x16x32_bf16 v[60:63], v[176:179], v[194:197], v[60:63]
	v_mfma_f32_16x16x32_bf16 v[56:59], v[184:187], v[194:197], v[56:59]
	v_mfma_f32_16x16x32_bf16 v[44:47], v[176:179], v[202:205], v[44:47]
	v_mfma_f32_16x16x32_bf16 v[40:43], v[184:187], v[202:205], v[40:43]
	v_mfma_f32_16x16x32_bf16 v[28:31], v[176:179], v[210:213], v[28:31]
	v_mfma_f32_16x16x32_bf16 v[24:27], v[184:187], v[210:213], v[24:27]
	v_mfma_f32_16x16x32_bf16 v[12:15], v[176:179], v[218:221], v[12:15]
	v_mfma_f32_16x16x32_bf16 v[4:7], v[184:187], v[218:221], v[4:7]
	s_barrier
	s_add_i32 s48, s48, 2
	s_add_u32 s20, s20, 0x100
	s_addc_u32 s21, s21, 0
	s_add_u32 s46, s46, 0x100
	s_addc_u32 s47, s47, 0
	s_cmp_gt_u32 s48, 29
	s_cbranch_scc0 .LBB0_664
	s_and_b64 vcc, exec, s[8:9]
	s_cbranch_vccz .LBB0_667
	s_barrier

.LBB0_749:
	ds_read_b128 v[128:131], v179
	ds_read_b128 v[132:135], v179 offset:1024
	ds_read_b128 v[136:139], v179 offset:2048
	ds_read_b128 v[140:143], v179 offset:3072
	ds_read_b128 v[160:163], v180
	ds_read_b128 v[164:167], v180 offset:1024
	ds_read_b128 v[168:171], v180 offset:2048
	ds_read_b128 v[172:175], v180 offset:3072
	s_add_u32 s20, s10, 0xffea0080
	s_addc_u32 s21, s11, -1
	s_cmpk_eq_i32 s48, 0x54
	s_cselect_b32 s23, s1, s21
	s_cselect_b32 s22, s0, s20
	s_cselect_b32 s21, s19, s47
	s_cselect_b32 s20, s18, s46
	v_lshl_add_u64 v[218:219], s[10:11], 0, v[152:153]
	s_add_i32 m0, s27, 0xc000
	ds_read_b128 v[184:187], v181
	ds_read_b128 v[190:193], v181 offset:1024
	ds_read_b128 v[194:197], v181 offset:2048
	ds_read_b128 v[198:201], v181 offset:3072
	ds_read_b128 v[202:205], v181 offset:4096
	ds_read_b128 v[206:209], v181 offset:5120
	ds_read_b128 v[210:213], v181 offset:6144
	ds_read_b128 v[214:217], v181 offset:7168
	global_load_lds_dwordx4 v[218:219], off
	v_lshl_add_u64 v[218:219], s[10:11], 0, v[154:155]
	s_add_i32 m0, s27, 0xe000
	s_nop 0
	global_load_lds_dwordx4 v[218:219], off
	s_waitcnt vmcnt(8)
	s_waitcnt lgkmcnt(0)
	s_barrier
	v_mfma_f32_16x16x32_bf16 v[124:127], v[128:131], v[184:187], v[124:127]
	v_mfma_f32_16x16x32_bf16 v[120:123], v[136:139], v[184:187], v[120:123]
	v_mfma_f32_16x16x32_bf16 v[108:111], v[128:131], v[194:197], v[108:111]
	v_mfma_f32_16x16x32_bf16 v[104:107], v[136:139], v[194:197], v[104:107]
	v_mfma_f32_16x16x32_bf16 v[92:95], v[128:131], v[202:205], v[92:95]
	v_mfma_f32_16x16x32_bf16 v[88:91], v[136:139], v[202:205], v[88:91]
	v_mfma_f32_16x16x32_bf16 v[76:79], v[128:131], v[210:213], v[76:79]
	v_mfma_f32_16x16x32_bf16 v[72:75], v[136:139], v[210:213], v[72:75]
	v_mfma_f32_16x16x32_bf16 v[124:127], v[132:135], v[190:193], v[124:127]
	v_mfma_f32_16x16x32_bf16 v[120:123], v[140:143], v[190:193], v[120:123]
	v_mfma_f32_16x16x32_bf16 v[108:111], v[132:135], v[198:201], v[108:111]
	v_mfma_f32_16x16x32_bf16 v[104:107], v[140:143], v[198:201], v[104:107]
	v_mfma_f32_16x16x32_bf16 v[92:95], v[132:135], v[206:209], v[92:95]
	v_mfma_f32_16x16x32_bf16 v[88:91], v[140:143], v[206:209], v[88:91]
	v_mfma_f32_16x16x32_bf16 v[76:79], v[132:135], v[214:217], v[76:79]
	v_mfma_f32_16x16x32_bf16 v[72:75], v[140:143], v[214:217], v[72:75]
	v_mfma_f32_16x16x32_bf16 v[116:119], v[160:163], v[184:187], v[116:119]
	v_mfma_f32_16x16x32_bf16 v[112:115], v[168:171], v[184:187], v[112:115]
	v_mfma_f32_16x16x32_bf16 v[100:103], v[160:163], v[194:197], v[100:103]
	v_mfma_f32_16x16x32_bf16 v[96:99], v[168:171], v[194:197], v[96:99]
	v_mfma_f32_16x16x32_bf16 v[84:87], v[160:163], v[202:205], v[84:87]
	v_mfma_f32_16x16x32_bf16 v[80:83], v[168:171], v[202:205], v[80:83]
	v_mfma_f32_16x16x32_bf16 v[68:71], v[160:163], v[210:213], v[68:71]
	v_mfma_f32_16x16x32_bf16 v[64:67], v[168:171], v[210:213], v[64:67]
	v_mfma_f32_16x16x32_bf16 v[116:119], v[164:167], v[190:193], v[116:119]
	v_mfma_f32_16x16x32_bf16 v[112:115], v[172:175], v[190:193], v[112:115]
	v_mfma_f32_16x16x32_bf16 v[100:103], v[164:167], v[198:201], v[100:103]
	v_mfma_f32_16x16x32_bf16 v[96:99], v[172:175], v[198:201], v[96:99]
	v_mfma_f32_16x16x32_bf16 v[84:87], v[164:167], v[206:209], v[84:87]
	v_mfma_f32_16x16x32_bf16 v[80:83], v[172:175], v[206:209], v[80:83]
	v_mfma_f32_16x16x32_bf16 v[68:71], v[164:167], v[214:217], v[68:71]
	v_mfma_f32_16x16x32_bf16 v[64:67], v[172:175], v[214:217], v[64:67]
	s_barrier
	s_add_i32 s49, s39, s26
	v_lshl_add_u64 v[218:219], s[20:21], 0, v[146:147]
	s_mov_b32 m0, s49
	ds_read_b128 v[184:187], v181 offset:16384
	ds_read_b128 v[190:193], v181 offset:17408
	ds_read_b128 v[194:197], v181 offset:18432
	ds_read_b128 v[198:201], v181 offset:19456
	ds_read_b128 v[202:205], v181 offset:20480
	ds_read_b128 v[206:209], v181 offset:21504
	ds_read_b128 v[210:213], v181 offset:22528
	ds_read_b128 v[214:217], v181 offset:23552
	global_load_lds_dwordx4 v[218:219], off
	s_add_i32 m0, s49, 0x2000
	s_add_u32 s50, s20, 0x160000
	v_lshl_add_u64 v[220:221], s[20:21], 0, v[150:151]
	s_addc_u32 s51, s21, 0
	s_add_i32 s49, s40, s26
	global_load_lds_dwordx4 v[220:221], off
	v_lshl_add_u64 v[222:223], s[50:51], 0, v[146:147]
	s_mov_b32 m0, s49
	v_lshl_add_u64 v[224:225], s[22:23], 0, v[148:149]
	global_load_lds_dwordx4 v[222:223], off
	v_lshl_add_u64 v[222:223], s[50:51], 0, v[150:151]
	s_add_i32 m0, s49, 0x2000
	s_nop 0
	global_load_lds_dwordx4 v[222:223], off
	v_lshl_add_u64 v[222:223], s[22:23], 0, v[144:145]
	s_mov_b32 m0, s27
	s_nop 0
	global_load_lds_dwordx4 v[222:223], off
	s_mov_b32 m0, s28
	s_nop 0
	global_load_lds_dwordx4 v[224:225], off
	s_waitcnt vmcnt(8)
	s_waitcnt lgkmcnt(0)
	s_barrier
	v_mfma_f32_16x16x32_bf16 v[60:63], v[128:131], v[184:187], v[60:63]
	v_mfma_f32_16x16x32_bf16 v[56:59], v[136:139], v[184:187], v[56:59]
	v_mfma_f32_16x16x32_bf16 v[44:47], v[128:131], v[194:197], v[44:47]
	v_mfma_f32_16x16x32_bf16 v[40:43], v[136:139], v[194:197], v[40:43]
	v_mfma_f32_16x16x32_bf16 v[28:31], v[128:131], v[202:205], v[28:31]
	v_mfma_f32_16x16x32_bf16 v[24:27], v[136:139], v[202:205], v[24:27]
	v_mfma_f32_16x16x32_bf16 v[12:15], v[128:131], v[210:213], v[12:15]
	v_mfma_f32_16x16x32_bf16 v[8:11], v[136:139], v[210:213], v[8:11]
	v_mfma_f32_16x16x32_bf16 v[60:63], v[132:135], v[190:193], v[60:63]
	v_mfma_f32_16x16x32_bf16 v[56:59], v[140:143], v[190:193], v[56:59]
	v_mfma_f32_16x16x32_bf16 v[44:47], v[132:135], v[198:201], v[44:47]
	v_mfma_f32_16x16x32_bf16 v[40:43], v[140:143], v[198:201], v[40:43]
	v_mfma_f32_16x16x32_bf16 v[28:31], v[132:135], v[206:209], v[28:31]
	v_mfma_f32_16x16x32_bf16 v[24:27], v[140:143], v[206:209], v[24:27]
	v_mfma_f32_16x16x32_bf16 v[12:15], v[132:135], v[214:217], v[12:15]
	v_mfma_f32_16x16x32_bf16 v[8:11], v[140:143], v[214:217], v[8:11]
	v_mfma_f32_16x16x32_bf16 v[52:55], v[160:163], v[184:187], v[52:55]
	v_mfma_f32_16x16x32_bf16 v[48:51], v[168:171], v[184:187], v[48:51]
	v_mfma_f32_16x16x32_bf16 v[36:39], v[160:163], v[194:197], v[36:39]
	v_mfma_f32_16x16x32_bf16 v[32:35], v[168:171], v[194:197], v[32:35]
	v_mfma_f32_16x16x32_bf16 v[20:23], v[160:163], v[202:205], v[20:23]
	v_mfma_f32_16x16x32_bf16 v[16:19], v[168:171], v[202:205], v[16:19]
	v_mfma_f32_16x16x32_bf16 v[4:7], v[160:163], v[210:213], v[4:7]
	v_mfma_f32_16x16x32_bf16 v[0:3], v[168:171], v[210:213], v[0:3]
	v_mfma_f32_16x16x32_bf16 v[52:55], v[164:167], v[190:193], v[52:55]
	v_mfma_f32_16x16x32_bf16 v[48:51], v[172:175], v[190:193], v[48:51]
	v_mfma_f32_16x16x32_bf16 v[36:39], v[164:167], v[198:201], v[36:39]
	v_mfma_f32_16x16x32_bf16 v[32:35], v[172:175], v[198:201], v[32:35]
	v_mfma_f32_16x16x32_bf16 v[20:23], v[164:167], v[206:209], v[20:23]
	v_mfma_f32_16x16x32_bf16 v[16:19], v[172:175], v[206:209], v[16:19]
	v_mfma_f32_16x16x32_bf16 v[4:7], v[164:167], v[214:217], v[4:7]
	v_mfma_f32_16x16x32_bf16 v[0:3], v[172:175], v[214:217], v[0:3]
	s_barrier
	s_add_i32 s49, 0, 0x18000
	s_add_i32 s50, 0, 0x1c000
	v_add_u32_e32 v140, s49, v177
	v_add_u32_e32 v172, s50, v177
	ds_read_b128 v[128:131], v140
	ds_read_b128 v[132:135], v140 offset:1024
	ds_read_b128 v[136:139], v140 offset:2048
	ds_read_b128 v[140:143], v140 offset:3072
	ds_read_b128 v[160:163], v172
	ds_read_b128 v[164:167], v172 offset:1024
	ds_read_b128 v[168:171], v172 offset:2048
	ds_read_b128 v[172:175], v172 offset:3072
	s_add_u32 s22, s22, 0x160000
	s_addc_u32 s23, s23, 0
	s_mov_b32 m0, s29
	v_lshl_add_u64 v[226:227], s[22:23], 0, v[144:145]
	ds_read_b128 v[184:187], v181 offset:32768
	ds_read_b128 v[190:193], v181 offset:33792
	ds_read_b128 v[194:197], v181 offset:34816
	ds_read_b128 v[198:201], v181 offset:35840
	ds_read_b128 v[202:205], v181 offset:36864
	ds_read_b128 v[206:209], v181 offset:37888
	ds_read_b128 v[210:213], v181 offset:38912
	ds_read_b128 v[214:217], v181 offset:39936
	global_load_lds_dwordx4 v[226:227], off
	v_lshl_add_u64 v[226:227], s[22:23], 0, v[148:149]
	s_mov_b32 m0, s30
	s_nop 0
	global_load_lds_dwordx4 v[226:227], off
	s_waitcnt vmcnt(8)
	s_waitcnt lgkmcnt(0)
	s_barrier
	v_mfma_f32_16x16x32_bf16 v[124:127], v[128:131], v[184:187], v[124:127]
	v_mfma_f32_16x16x32_bf16 v[120:123], v[136:139], v[184:187], v[120:123]
	v_mfma_f32_16x16x32_bf16 v[108:111], v[128:131], v[194:197], v[108:111]
	v_mfma_f32_16x16x32_bf16 v[104:107], v[136:139], v[194:197], v[104:107]
	v_mfma_f32_16x16x32_bf16 v[92:95], v[128:131], v[202:205], v[92:95]
	v_mfma_f32_16x16x32_bf16 v[88:91], v[136:139], v[202:205], v[88:91]
	v_mfma_f32_16x16x32_bf16 v[76:79], v[128:131], v[210:213], v[76:79]
	v_mfma_f32_16x16x32_bf16 v[72:75], v[136:139], v[210:213], v[72:75]
	v_mfma_f32_16x16x32_bf16 v[124:127], v[132:135], v[190:193], v[124:127]
	v_mfma_f32_16x16x32_bf16 v[120:123], v[140:143], v[190:193], v[120:123]
	v_mfma_f32_16x16x32_bf16 v[108:111], v[132:135], v[198:201], v[108:111]
	v_mfma_f32_16x16x32_bf16 v[104:107], v[140:143], v[198:201], v[104:107]
	v_mfma_f32_16x16x32_bf16 v[92:95], v[132:135], v[206:209], v[92:95]
	v_mfma_f32_16x16x32_bf16 v[88:91], v[140:143], v[206:209], v[88:91]
	v_mfma_f32_16x16x32_bf16 v[76:79], v[132:135], v[214:217], v[76:79]
	v_mfma_f32_16x16x32_bf16 v[72:75], v[140:143], v[214:217], v[72:75]
	v_mfma_f32_16x16x32_bf16 v[116:119], v[160:163], v[184:187], v[116:119]
	v_mfma_f32_16x16x32_bf16 v[112:115], v[168:171], v[184:187], v[112:115]
	v_mfma_f32_16x16x32_bf16 v[100:103], v[160:163], v[194:197], v[100:103]
	v_mfma_f32_16x16x32_bf16 v[96:99], v[168:171], v[194:197], v[96:99]
	v_mfma_f32_16x16x32_bf16 v[84:87], v[160:163], v[202:205], v[84:87]
	v_mfma_f32_16x16x32_bf16 v[80:83], v[168:171], v[202:205], v[80:83]
	v_mfma_f32_16x16x32_bf16 v[68:71], v[160:163], v[210:213], v[68:71]
	v_mfma_f32_16x16x32_bf16 v[64:67], v[168:171], v[210:213], v[64:67]
	v_mfma_f32_16x16x32_bf16 v[116:119], v[164:167], v[190:193], v[116:119]
	v_mfma_f32_16x16x32_bf16 v[112:115], v[172:175], v[190:193], v[112:115]
	v_mfma_f32_16x16x32_bf16 v[100:103], v[164:167], v[198:201], v[100:103]
	v_mfma_f32_16x16x32_bf16 v[96:99], v[172:175], v[198:201], v[96:99]
	v_mfma_f32_16x16x32_bf16 v[84:87], v[164:167], v[206:209], v[84:87]
	v_mfma_f32_16x16x32_bf16 v[80:83], v[172:175], v[206:209], v[80:83]
	v_mfma_f32_16x16x32_bf16 v[68:71], v[164:167], v[214:217], v[68:71]
	v_mfma_f32_16x16x32_bf16 v[64:67], v[172:175], v[214:217], v[64:67]
	s_barrier
	s_add_i32 s22, s49, s26
	v_lshl_add_u64 v[218:219], v[218:219], 0, s[12:13]
	s_mov_b32 m0, s22
	ds_read_b128 v[184:187], v181 offset:49152
	ds_read_b128 v[190:193], v181 offset:50176
	ds_read_b128 v[194:197], v181 offset:51200
	ds_read_b128 v[198:201], v181 offset:52224
	ds_read_b128 v[202:205], v181 offset:53248
	ds_read_b128 v[206:209], v181 offset:54272
	ds_read_b128 v[210:213], v181 offset:55296
	ds_read_b128 v[214:217], v181 offset:56320
	global_load_lds_dwordx4 v[218:219], off
	s_add_i32 m0, s22, 0x2000
	s_add_u32 s20, s20, 0x160080
	v_lshl_add_u64 v[218:219], v[220:221], 0, s[12:13]
	s_addc_u32 s21, s21, 0
	s_add_i32 s22, s50, s26
	global_load_lds_dwordx4 v[218:219], off
	v_lshl_add_u64 v[218:219], s[20:21], 0, v[146:147]
	s_mov_b32 m0, s22
	s_nop 0
	global_load_lds_dwordx4 v[218:219], off
	v_lshl_add_u64 v[218:219], s[20:21], 0, v[150:151]
	s_add_i32 m0, s22, 0x2000
	s_nop 0
	global_load_lds_dwordx4 v[218:219], off
	v_lshl_add_u64 v[218:219], v[222:223], 0, s[12:13]
	s_mov_b32 m0, s35
	s_nop 0
	global_load_lds_dwordx4 v[218:219], off
	v_lshl_add_u64 v[218:219], v[224:225], 0, s[12:13]
	s_mov_b32 m0, s36
	s_nop 0
	global_load_lds_dwordx4 v[218:219], off
	s_waitcnt vmcnt(8)
	s_waitcnt lgkmcnt(0)
	s_barrier
	v_mfma_f32_16x16x32_bf16 v[60:63], v[128:131], v[184:187], v[60:63]
	v_mfma_f32_16x16x32_bf16 v[56:59], v[136:139], v[184:187], v[56:59]
	v_mfma_f32_16x16x32_bf16 v[44:47], v[128:131], v[194:197], v[44:47]
	v_mfma_f32_16x16x32_bf16 v[40:43], v[136:139], v[194:197], v[40:43]
	v_mfma_f32_16x16x32_bf16 v[28:31], v[128:131], v[202:205], v[28:31]
	v_mfma_f32_16x16x32_bf16 v[24:27], v[136:139], v[202:205], v[24:27]
	v_mfma_f32_16x16x32_bf16 v[12:15], v[128:131], v[210:213], v[12:15]
	v_mfma_f32_16x16x32_bf16 v[8:11], v[136:139], v[210:213], v[8:11]
	v_mfma_f32_16x16x32_bf16 v[60:63], v[132:135], v[190:193], v[60:63]
	v_mfma_f32_16x16x32_bf16 v[56:59], v[140:143], v[190:193], v[56:59]
	v_mfma_f32_16x16x32_bf16 v[44:47], v[132:135], v[198:201], v[44:47]
	v_mfma_f32_16x16x32_bf16 v[40:43], v[140:143], v[198:201], v[40:43]
	v_mfma_f32_16x16x32_bf16 v[28:31], v[132:135], v[206:209], v[28:31]
	v_mfma_f32_16x16x32_bf16 v[24:27], v[140:143], v[206:209], v[24:27]
	v_mfma_f32_16x16x32_bf16 v[12:15], v[132:135], v[214:217], v[12:15]
	v_mfma_f32_16x16x32_bf16 v[8:11], v[140:143], v[214:217], v[8:11]
	v_mfma_f32_16x16x32_bf16 v[52:55], v[160:163], v[184:187], v[52:55]
	v_mfma_f32_16x16x32_bf16 v[48:51], v[168:171], v[184:187], v[48:51]
	v_mfma_f32_16x16x32_bf16 v[36:39], v[160:163], v[194:197], v[36:39]
	v_mfma_f32_16x16x32_bf16 v[32:35], v[168:171], v[194:197], v[32:35]
	v_mfma_f32_16x16x32_bf16 v[20:23], v[160:163], v[202:205], v[20:23]
	v_mfma_f32_16x16x32_bf16 v[16:19], v[168:171], v[202:205], v[16:19]
	v_mfma_f32_16x16x32_bf16 v[4:7], v[160:163], v[210:213], v[4:7]
	v_mfma_f32_16x16x32_bf16 v[0:3], v[168:171], v[210:213], v[0:3]
	v_mfma_f32_16x16x32_bf16 v[52:55], v[164:167], v[190:193], v[52:55]
	v_mfma_f32_16x16x32_bf16 v[48:51], v[172:175], v[190:193], v[48:51]
	v_mfma_f32_16x16x32_bf16 v[36:39], v[164:167], v[198:201], v[36:39]
	v_mfma_f32_16x16x32_bf16 v[32:35], v[172:175], v[198:201], v[32:35]
	v_mfma_f32_16x16x32_bf16 v[20:23], v[164:167], v[206:209], v[20:23]
	v_mfma_f32_16x16x32_bf16 v[16:19], v[172:175], v[206:209], v[16:19]
	v_mfma_f32_16x16x32_bf16 v[4:7], v[164:167], v[214:217], v[4:7]
	v_mfma_f32_16x16x32_bf16 v[0:3], v[172:175], v[214:217], v[0:3]
	s_barrier
	s_add_i32 s48, s48, 2
	s_add_u32 s10, s10, 0x100
	s_addc_u32 s11, s11, 0
	s_add_u32 s46, s46, 0x100
	s_addc_u32 s47, s47, 0
	s_cmpk_gt_u32 s48, 0x55
	s_cbranch_scc0 .LBB0_749
	s_and_b64 vcc, exec, s[14:15]
	s_cbranch_vccz .LBB0_752
	s_barrier

.LBB0_838:
	ds_read_b128 v[154:157], v143
	ds_read_b128 v[164:167], v143 offset:1024
	ds_read_b128 v[168:171], v143 offset:2048
	ds_read_b128 v[172:175], v143 offset:3072
	ds_read_b128 v[176:179], v160
	ds_read_b128 v[180:183], v160 offset:1024
	ds_read_b128 v[184:187], v160 offset:2048
	ds_read_b128 v[190:193], v160 offset:3072
	s_add_u32 s44, s10, 0xfff80080
	s_addc_u32 s45, s11, -1
	s_cmp_eq_u32 s62, 28
	s_cselect_b32 s47, s7, s45
	s_cselect_b32 s46, s35, s44
	s_cselect_b32 s45, s37, s61
	s_cselect_b32 s44, s59, s60
	v_lshl_add_u64 v[226:227], s[10:11], 0, v[146:147]
	s_add_i32 m0, s27, 0xc000
	ds_read_b128 v[194:197], v161
	ds_read_b128 v[198:201], v161 offset:1024
	ds_read_b128 v[202:205], v161 offset:2048
	ds_read_b128 v[206:209], v161 offset:3072
	ds_read_b128 v[210:213], v161 offset:4096
	ds_read_b128 v[214:217], v161 offset:5120
	ds_read_b128 v[218:221], v161 offset:6144
	ds_read_b128 v[222:225], v161 offset:7168
	global_load_lds_dwordx4 v[226:227], off
	v_lshl_add_u64 v[226:227], s[10:11], 0, v[148:149]
	s_add_i32 m0, s27, 0xe000
	s_nop 0
	global_load_lds_dwordx4 v[226:227], off
	s_waitcnt vmcnt(8)
	s_waitcnt lgkmcnt(0)
	s_barrier
	v_mfma_f32_16x16x32_bf16 v[124:127], v[154:157], v[194:197], v[124:127]
	v_mfma_f32_16x16x32_bf16 v[120:123], v[168:171], v[194:197], v[120:123]
	v_mfma_f32_16x16x32_bf16 v[108:111], v[154:157], v[202:205], v[108:111]
	v_mfma_f32_16x16x32_bf16 v[104:107], v[168:171], v[202:205], v[104:107]
	v_mfma_f32_16x16x32_bf16 v[92:95], v[154:157], v[210:213], v[92:95]
	v_mfma_f32_16x16x32_bf16 v[88:91], v[168:171], v[210:213], v[88:91]
	v_mfma_f32_16x16x32_bf16 v[76:79], v[154:157], v[218:221], v[76:79]
	v_mfma_f32_16x16x32_bf16 v[72:75], v[168:171], v[218:221], v[72:75]
	v_mfma_f32_16x16x32_bf16 v[124:127], v[164:167], v[198:201], v[124:127]
	v_mfma_f32_16x16x32_bf16 v[120:123], v[172:175], v[198:201], v[120:123]
	v_mfma_f32_16x16x32_bf16 v[108:111], v[164:167], v[206:209], v[108:111]
	v_mfma_f32_16x16x32_bf16 v[104:107], v[172:175], v[206:209], v[104:107]
	v_mfma_f32_16x16x32_bf16 v[92:95], v[164:167], v[214:217], v[92:95]
	v_mfma_f32_16x16x32_bf16 v[88:91], v[172:175], v[214:217], v[88:91]
	v_mfma_f32_16x16x32_bf16 v[76:79], v[164:167], v[222:225], v[76:79]
	v_mfma_f32_16x16x32_bf16 v[72:75], v[172:175], v[222:225], v[72:75]
	v_mfma_f32_16x16x32_bf16 v[116:119], v[176:179], v[194:197], v[116:119]
	v_mfma_f32_16x16x32_bf16 v[112:115], v[184:187], v[194:197], v[112:115]
	v_mfma_f32_16x16x32_bf16 v[100:103], v[176:179], v[202:205], v[100:103]
	v_mfma_f32_16x16x32_bf16 v[96:99], v[184:187], v[202:205], v[96:99]
	v_mfma_f32_16x16x32_bf16 v[84:87], v[176:179], v[210:213], v[84:87]
	v_mfma_f32_16x16x32_bf16 v[80:83], v[184:187], v[210:213], v[80:83]
	v_mfma_f32_16x16x32_bf16 v[68:71], v[176:179], v[218:221], v[68:71]
	v_mfma_f32_16x16x32_bf16 v[64:67], v[184:187], v[218:221], v[64:67]
	v_mfma_f32_16x16x32_bf16 v[116:119], v[180:183], v[198:201], v[116:119]
	v_mfma_f32_16x16x32_bf16 v[112:115], v[190:193], v[198:201], v[112:115]
	v_mfma_f32_16x16x32_bf16 v[100:103], v[180:183], v[206:209], v[100:103]
	v_mfma_f32_16x16x32_bf16 v[96:99], v[190:193], v[206:209], v[96:99]
	v_mfma_f32_16x16x32_bf16 v[84:87], v[180:183], v[214:217], v[84:87]
	v_mfma_f32_16x16x32_bf16 v[80:83], v[190:193], v[214:217], v[80:83]
	v_mfma_f32_16x16x32_bf16 v[68:71], v[180:183], v[222:225], v[68:71]
	v_mfma_f32_16x16x32_bf16 v[64:67], v[190:193], v[222:225], v[64:67]
	s_barrier
	s_add_i32 s63, s54, s26
	v_lshl_add_u64 v[226:227], s[44:45], 0, v[130:131]
	s_mov_b32 m0, s63
	ds_read_b128 v[194:197], v161 offset:16384
	ds_read_b128 v[198:201], v161 offset:17408
	ds_read_b128 v[202:205], v161 offset:18432
	ds_read_b128 v[206:209], v161 offset:19456
	ds_read_b128 v[210:213], v161 offset:20480
	ds_read_b128 v[214:217], v161 offset:21504
	ds_read_b128 v[218:221], v161 offset:22528
	ds_read_b128 v[222:225], v161 offset:23552
	global_load_lds_dwordx4 v[226:227], off
	s_add_i32 m0, s63, 0x2000
	s_add_u32 s64, s44, 0x80000
	v_lshl_add_u64 v[228:229], s[44:45], 0, v[134:135]
	s_addc_u32 s65, s45, 0
	s_add_i32 s63, s55, s26
	global_load_lds_dwordx4 v[228:229], off
	v_lshl_add_u64 v[230:231], s[64:65], 0, v[130:131]
	s_mov_b32 m0, s63
	v_lshl_add_u64 v[232:233], s[46:47], 0, v[132:133]
	global_load_lds_dwordx4 v[230:231], off
	v_lshl_add_u64 v[230:231], s[64:65], 0, v[134:135]
	s_add_i32 m0, s63, 0x2000
	s_nop 0
	global_load_lds_dwordx4 v[230:231], off
	v_lshl_add_u64 v[230:231], s[46:47], 0, v[128:129]
	s_mov_b32 m0, s27
	s_nop 0
	global_load_lds_dwordx4 v[230:231], off
	s_mov_b32 m0, s28
	s_nop 0
	global_load_lds_dwordx4 v[232:233], off
	s_waitcnt vmcnt(8)
	s_waitcnt lgkmcnt(0)
	s_barrier
	v_mfma_f32_16x16x32_bf16 v[60:63], v[154:157], v[194:197], v[60:63]
	v_mfma_f32_16x16x32_bf16 v[56:59], v[168:171], v[194:197], v[56:59]
	v_mfma_f32_16x16x32_bf16 v[44:47], v[154:157], v[202:205], v[44:47]
	v_mfma_f32_16x16x32_bf16 v[40:43], v[168:171], v[202:205], v[40:43]
	v_mfma_f32_16x16x32_bf16 v[28:31], v[154:157], v[210:213], v[28:31]
	v_mfma_f32_16x16x32_bf16 v[24:27], v[168:171], v[210:213], v[24:27]
	v_mfma_f32_16x16x32_bf16 v[12:15], v[154:157], v[218:221], v[12:15]
	v_mfma_f32_16x16x32_bf16 v[8:11], v[168:171], v[218:221], v[8:11]
	v_mfma_f32_16x16x32_bf16 v[60:63], v[164:167], v[198:201], v[60:63]
	v_mfma_f32_16x16x32_bf16 v[56:59], v[172:175], v[198:201], v[56:59]
	v_mfma_f32_16x16x32_bf16 v[44:47], v[164:167], v[206:209], v[44:47]
	v_mfma_f32_16x16x32_bf16 v[40:43], v[172:175], v[206:209], v[40:43]
	v_mfma_f32_16x16x32_bf16 v[28:31], v[164:167], v[214:217], v[28:31]
	v_mfma_f32_16x16x32_bf16 v[24:27], v[172:175], v[214:217], v[24:27]
	v_mfma_f32_16x16x32_bf16 v[12:15], v[164:167], v[222:225], v[12:15]
	v_mfma_f32_16x16x32_bf16 v[8:11], v[172:175], v[222:225], v[8:11]
	v_mfma_f32_16x16x32_bf16 v[52:55], v[176:179], v[194:197], v[52:55]
	v_mfma_f32_16x16x32_bf16 v[48:51], v[184:187], v[194:197], v[48:51]
	v_mfma_f32_16x16x32_bf16 v[36:39], v[176:179], v[202:205], v[36:39]
	v_mfma_f32_16x16x32_bf16 v[32:35], v[184:187], v[202:205], v[32:35]
	v_mfma_f32_16x16x32_bf16 v[20:23], v[176:179], v[210:213], v[20:23]
	v_mfma_f32_16x16x32_bf16 v[16:19], v[184:187], v[210:213], v[16:19]
	v_mfma_f32_16x16x32_bf16 v[4:7], v[176:179], v[218:221], v[4:7]
	v_mfma_f32_16x16x32_bf16 v[0:3], v[184:187], v[218:221], v[0:3]
	v_mfma_f32_16x16x32_bf16 v[52:55], v[180:183], v[198:201], v[52:55]
	v_mfma_f32_16x16x32_bf16 v[48:51], v[190:193], v[198:201], v[48:51]
	v_mfma_f32_16x16x32_bf16 v[36:39], v[180:183], v[206:209], v[36:39]
	v_mfma_f32_16x16x32_bf16 v[32:35], v[190:193], v[206:209], v[32:35]
	v_mfma_f32_16x16x32_bf16 v[20:23], v[180:183], v[214:217], v[20:23]
	v_mfma_f32_16x16x32_bf16 v[16:19], v[190:193], v[214:217], v[16:19]
	v_mfma_f32_16x16x32_bf16 v[4:7], v[180:183], v[222:225], v[4:7]
	v_mfma_f32_16x16x32_bf16 v[0:3], v[190:193], v[222:225], v[0:3]
	s_barrier
	s_add_i32 s63, 0, 0x18000
	v_add_u32_e32 v136, s63, v159
	s_add_i32 s64, 0, 0x1c000
	ds_read_b128 v[154:157], v136
	ds_read_b128 v[164:167], v136 offset:1024
	ds_read_b128 v[168:171], v136 offset:2048
	ds_read_b128 v[172:175], v136 offset:3072
	v_add_u32_e32 v136, s64, v159
	ds_read_b128 v[176:179], v136
	ds_read_b128 v[180:183], v136 offset:1024
	ds_read_b128 v[184:187], v136 offset:2048
	ds_read_b128 v[190:193], v136 offset:3072
	s_add_u32 s46, s46, 0x80000
	s_addc_u32 s47, s47, 0
	s_mov_b32 m0, s29
	v_lshl_add_u64 v[234:235], s[46:47], 0, v[128:129]
	ds_read_b128 v[194:197], v161 offset:32768
	ds_read_b128 v[198:201], v161 offset:33792
	ds_read_b128 v[202:205], v161 offset:34816
	ds_read_b128 v[206:209], v161 offset:35840
	ds_read_b128 v[210:213], v161 offset:36864
	ds_read_b128 v[214:217], v161 offset:37888
	ds_read_b128 v[218:221], v161 offset:38912
	ds_read_b128 v[222:225], v161 offset:39936
	global_load_lds_dwordx4 v[234:235], off
	v_lshl_add_u64 v[234:235], s[46:47], 0, v[132:133]
	s_mov_b32 m0, s33
	s_nop 0
	global_load_lds_dwordx4 v[234:235], off
	s_waitcnt vmcnt(8)
	s_waitcnt lgkmcnt(0)
	s_barrier
	v_mfma_f32_16x16x32_bf16 v[124:127], v[154:157], v[194:197], v[124:127]
	v_mfma_f32_16x16x32_bf16 v[120:123], v[168:171], v[194:197], v[120:123]
	v_mfma_f32_16x16x32_bf16 v[108:111], v[154:157], v[202:205], v[108:111]
	v_mfma_f32_16x16x32_bf16 v[104:107], v[168:171], v[202:205], v[104:107]
	v_mfma_f32_16x16x32_bf16 v[92:95], v[154:157], v[210:213], v[92:95]
	v_mfma_f32_16x16x32_bf16 v[88:91], v[168:171], v[210:213], v[88:91]
	v_mfma_f32_16x16x32_bf16 v[76:79], v[154:157], v[218:221], v[76:79]
	v_mfma_f32_16x16x32_bf16 v[72:75], v[168:171], v[218:221], v[72:75]
	v_mfma_f32_16x16x32_bf16 v[124:127], v[164:167], v[198:201], v[124:127]
	v_mfma_f32_16x16x32_bf16 v[120:123], v[172:175], v[198:201], v[120:123]
	v_mfma_f32_16x16x32_bf16 v[108:111], v[164:167], v[206:209], v[108:111]
	v_mfma_f32_16x16x32_bf16 v[104:107], v[172:175], v[206:209], v[104:107]
	v_mfma_f32_16x16x32_bf16 v[92:95], v[164:167], v[214:217], v[92:95]
	v_mfma_f32_16x16x32_bf16 v[88:91], v[172:175], v[214:217], v[88:91]
	v_mfma_f32_16x16x32_bf16 v[76:79], v[164:167], v[222:225], v[76:79]
	v_mfma_f32_16x16x32_bf16 v[72:75], v[172:175], v[222:225], v[72:75]
	v_mfma_f32_16x16x32_bf16 v[116:119], v[176:179], v[194:197], v[116:119]
	v_mfma_f32_16x16x32_bf16 v[112:115], v[184:187], v[194:197], v[112:115]
	v_mfma_f32_16x16x32_bf16 v[100:103], v[176:179], v[202:205], v[100:103]
	v_mfma_f32_16x16x32_bf16 v[96:99], v[184:187], v[202:205], v[96:99]
	v_mfma_f32_16x16x32_bf16 v[84:87], v[176:179], v[210:213], v[84:87]
	v_mfma_f32_16x16x32_bf16 v[80:83], v[184:187], v[210:213], v[80:83]
	v_mfma_f32_16x16x32_bf16 v[68:71], v[176:179], v[218:221], v[68:71]
	v_mfma_f32_16x16x32_bf16 v[64:67], v[184:187], v[218:221], v[64:67]
	v_mfma_f32_16x16x32_bf16 v[116:119], v[180:183], v[198:201], v[116:119]
	v_mfma_f32_16x16x32_bf16 v[112:115], v[190:193], v[198:201], v[112:115]
	v_mfma_f32_16x16x32_bf16 v[100:103], v[180:183], v[206:209], v[100:103]
	v_mfma_f32_16x16x32_bf16 v[96:99], v[190:193], v[206:209], v[96:99]
	v_mfma_f32_16x16x32_bf16 v[84:87], v[180:183], v[214:217], v[84:87]
	v_mfma_f32_16x16x32_bf16 v[80:83], v[190:193], v[214:217], v[80:83]
	v_mfma_f32_16x16x32_bf16 v[68:71], v[180:183], v[222:225], v[68:71]
	v_mfma_f32_16x16x32_bf16 v[64:67], v[190:193], v[222:225], v[64:67]
	s_barrier
	s_add_i32 s46, s63, s26
	v_lshl_add_u64 v[226:227], v[226:227], 0, s[18:19]
	s_mov_b32 m0, s46
	ds_read_b128 v[194:197], v161 offset:49152
	ds_read_b128 v[198:201], v161 offset:50176
	ds_read_b128 v[202:205], v161 offset:51200
	ds_read_b128 v[206:209], v161 offset:52224
	ds_read_b128 v[210:213], v161 offset:53248
	ds_read_b128 v[214:217], v161 offset:54272
	ds_read_b128 v[218:221], v161 offset:55296
	ds_read_b128 v[222:225], v161 offset:56320
	global_load_lds_dwordx4 v[226:227], off
	s_add_i32 m0, s46, 0x2000
	s_add_u32 s44, s44, 0x80080
	v_lshl_add_u64 v[226:227], v[228:229], 0, s[18:19]
	s_addc_u32 s45, s45, 0
	s_add_i32 s46, s64, s26
	global_load_lds_dwordx4 v[226:227], off
	v_lshl_add_u64 v[226:227], s[44:45], 0, v[130:131]
	s_mov_b32 m0, s46
	s_nop 0
	global_load_lds_dwordx4 v[226:227], off
	v_lshl_add_u64 v[226:227], s[44:45], 0, v[134:135]
	s_add_i32 m0, s46, 0x2000
	s_nop 0
	global_load_lds_dwordx4 v[226:227], off
	v_lshl_add_u64 v[226:227], v[230:231], 0, s[18:19]
	s_mov_b32 m0, s50
	s_nop 0
	global_load_lds_dwordx4 v[226:227], off
	v_lshl_add_u64 v[226:227], v[232:233], 0, s[18:19]
	s_mov_b32 m0, s51
	s_nop 0
	global_load_lds_dwordx4 v[226:227], off
	s_waitcnt vmcnt(8)
	s_waitcnt lgkmcnt(0)
	s_barrier
	v_mfma_f32_16x16x32_bf16 v[60:63], v[154:157], v[194:197], v[60:63]
	v_mfma_f32_16x16x32_bf16 v[56:59], v[168:171], v[194:197], v[56:59]
	v_mfma_f32_16x16x32_bf16 v[44:47], v[154:157], v[202:205], v[44:47]
	v_mfma_f32_16x16x32_bf16 v[40:43], v[168:171], v[202:205], v[40:43]
	v_mfma_f32_16x16x32_bf16 v[28:31], v[154:157], v[210:213], v[28:31]
	v_mfma_f32_16x16x32_bf16 v[24:27], v[168:171], v[210:213], v[24:27]
	v_mfma_f32_16x16x32_bf16 v[12:15], v[154:157], v[218:221], v[12:15]
	v_mfma_f32_16x16x32_bf16 v[8:11], v[168:171], v[218:221], v[8:11]
	v_mfma_f32_16x16x32_bf16 v[60:63], v[164:167], v[198:201], v[60:63]
	v_mfma_f32_16x16x32_bf16 v[56:59], v[172:175], v[198:201], v[56:59]
	v_mfma_f32_16x16x32_bf16 v[44:47], v[164:167], v[206:209], v[44:47]
	v_mfma_f32_16x16x32_bf16 v[40:43], v[172:175], v[206:209], v[40:43]
	v_mfma_f32_16x16x32_bf16 v[28:31], v[164:167], v[214:217], v[28:31]
	v_mfma_f32_16x16x32_bf16 v[24:27], v[172:175], v[214:217], v[24:27]
	v_mfma_f32_16x16x32_bf16 v[12:15], v[164:167], v[222:225], v[12:15]
	v_mfma_f32_16x16x32_bf16 v[8:11], v[172:175], v[222:225], v[8:11]
	v_mfma_f32_16x16x32_bf16 v[52:55], v[176:179], v[194:197], v[52:55]
	v_mfma_f32_16x16x32_bf16 v[48:51], v[184:187], v[194:197], v[48:51]
	v_mfma_f32_16x16x32_bf16 v[36:39], v[176:179], v[202:205], v[36:39]
	v_mfma_f32_16x16x32_bf16 v[32:35], v[184:187], v[202:205], v[32:35]
	v_mfma_f32_16x16x32_bf16 v[20:23], v[176:179], v[210:213], v[20:23]
	v_mfma_f32_16x16x32_bf16 v[16:19], v[184:187], v[210:213], v[16:19]
	v_mfma_f32_16x16x32_bf16 v[4:7], v[176:179], v[218:221], v[4:7]
	v_mfma_f32_16x16x32_bf16 v[0:3], v[184:187], v[218:221], v[0:3]
	v_mfma_f32_16x16x32_bf16 v[52:55], v[180:183], v[198:201], v[52:55]
	v_mfma_f32_16x16x32_bf16 v[48:51], v[190:193], v[198:201], v[48:51]
	v_mfma_f32_16x16x32_bf16 v[36:39], v[180:183], v[206:209], v[36:39]
	v_mfma_f32_16x16x32_bf16 v[32:35], v[190:193], v[206:209], v[32:35]
	v_mfma_f32_16x16x32_bf16 v[20:23], v[180:183], v[214:217], v[20:23]
	v_mfma_f32_16x16x32_bf16 v[16:19], v[190:193], v[214:217], v[16:19]
	v_mfma_f32_16x16x32_bf16 v[4:7], v[180:183], v[222:225], v[4:7]
	v_mfma_f32_16x16x32_bf16 v[0:3], v[190:193], v[222:225], v[0:3]
	s_barrier
	s_add_i32 s62, s62, 2
	s_add_u32 s10, s10, 0x100
	s_addc_u32 s11, s11, 0
	s_add_u32 s60, s60, 0x100
	s_addc_u32 s61, s61, 0
	s_cmp_gt_u32 s62, 29
	s_cbranch_scc0 .LBB0_838
	s_and_b64 vcc, exec, s[20:21]
	s_cbranch_vccnz .LBB0_843
	v_lshl_add_u32 v154, s6, 8, v158
	s_cmp_gt_i32 s42, 3
	s_mov_b64 s[6:7], -1
	s_cbranch_scc1 .LBB0_844

.LBB0_947:
	ds_read_b128 v[154:157], v137
	ds_read_b128 v[158:161], v137 offset:1024
	ds_read_b128 v[174:177], v137 offset:2048
	ds_read_b128 v[178:181], v137 offset:3072
	ds_read_b128 v[182:185], v170
	ds_read_b128 v[190:193], v170 offset:1024
	ds_read_b128 v[194:197], v170 offset:2048
	ds_read_b128 v[198:201], v170 offset:3072
	s_add_u32 s34, s10, 0xfffe0080
	s_addc_u32 s35, s11, -1
	s_cmp_eq_u32 s53, 4
	s_cselect_b32 s37, s5, s35
	s_cselect_b32 s36, s9, s34
	s_cselect_b32 s35, s13, s52
	s_cselect_b32 s34, s16, s51
	v_lshl_add_u64 v[186:187], s[10:11], 0, v[146:147]
	s_add_i32 m0, s15, 0xc000
	ds_read_b128 v[202:205], v171
	ds_read_b128 v[206:209], v171 offset:1024
	ds_read_b128 v[210:213], v171 offset:2048
	ds_read_b128 v[214:217], v171 offset:3072
	ds_read_b128 v[218:221], v171 offset:4096
	ds_read_b128 v[222:225], v171 offset:5120
	ds_read_b128 v[226:229], v171 offset:6144
	ds_read_b128 v[230:233], v171 offset:7168
	global_load_lds_dwordx4 v[186:187], off
	v_lshl_add_u64 v[186:187], s[10:11], 0, v[148:149]
	s_add_i32 m0, s15, 0xe000
	s_nop 0
	global_load_lds_dwordx4 v[186:187], off
	s_waitcnt vmcnt(8)
	s_waitcnt lgkmcnt(0)
	s_barrier
	v_mfma_f32_16x16x32_bf16 v[124:127], v[154:157], v[202:205], v[124:127]
	v_mfma_f32_16x16x32_bf16 v[120:123], v[174:177], v[202:205], v[120:123]
	v_mfma_f32_16x16x32_bf16 v[108:111], v[154:157], v[210:213], v[108:111]
	v_mfma_f32_16x16x32_bf16 v[104:107], v[174:177], v[210:213], v[104:107]
	v_mfma_f32_16x16x32_bf16 v[92:95], v[154:157], v[218:221], v[92:95]
	v_mfma_f32_16x16x32_bf16 v[88:91], v[174:177], v[218:221], v[88:91]
	v_mfma_f32_16x16x32_bf16 v[76:79], v[154:157], v[226:229], v[76:79]
	v_mfma_f32_16x16x32_bf16 v[72:75], v[174:177], v[226:229], v[72:75]
	v_mfma_f32_16x16x32_bf16 v[124:127], v[158:161], v[206:209], v[124:127]
	v_mfma_f32_16x16x32_bf16 v[120:123], v[178:181], v[206:209], v[120:123]
	v_mfma_f32_16x16x32_bf16 v[108:111], v[158:161], v[214:217], v[108:111]
	v_mfma_f32_16x16x32_bf16 v[104:107], v[178:181], v[214:217], v[104:107]
	v_mfma_f32_16x16x32_bf16 v[92:95], v[158:161], v[222:225], v[92:95]
	v_mfma_f32_16x16x32_bf16 v[88:91], v[178:181], v[222:225], v[88:91]
	v_mfma_f32_16x16x32_bf16 v[76:79], v[158:161], v[230:233], v[76:79]
	v_mfma_f32_16x16x32_bf16 v[72:75], v[178:181], v[230:233], v[72:75]
	v_mfma_f32_16x16x32_bf16 v[116:119], v[182:185], v[202:205], v[116:119]
	v_mfma_f32_16x16x32_bf16 v[112:115], v[194:197], v[202:205], v[112:115]
	v_mfma_f32_16x16x32_bf16 v[100:103], v[182:185], v[210:213], v[100:103]
	v_mfma_f32_16x16x32_bf16 v[96:99], v[194:197], v[210:213], v[96:99]
	v_mfma_f32_16x16x32_bf16 v[84:87], v[182:185], v[218:221], v[84:87]
	v_mfma_f32_16x16x32_bf16 v[80:83], v[194:197], v[218:221], v[80:83]
	v_mfma_f32_16x16x32_bf16 v[68:71], v[182:185], v[226:229], v[68:71]
	v_mfma_f32_16x16x32_bf16 v[64:67], v[194:197], v[226:229], v[64:67]
	v_mfma_f32_16x16x32_bf16 v[116:119], v[190:193], v[206:209], v[116:119]
	v_mfma_f32_16x16x32_bf16 v[112:115], v[198:201], v[206:209], v[112:115]
	v_mfma_f32_16x16x32_bf16 v[100:103], v[190:193], v[214:217], v[100:103]
	v_mfma_f32_16x16x32_bf16 v[96:99], v[198:201], v[214:217], v[96:99]
	v_mfma_f32_16x16x32_bf16 v[84:87], v[190:193], v[222:225], v[84:87]
	v_mfma_f32_16x16x32_bf16 v[80:83], v[198:201], v[222:225], v[80:83]
	v_mfma_f32_16x16x32_bf16 v[68:71], v[190:193], v[230:233], v[68:71]
	v_mfma_f32_16x16x32_bf16 v[64:67], v[198:201], v[230:233], v[64:67]
	s_barrier
	s_add_i32 s54, s47, s26
	v_lshl_add_u64 v[186:187], s[34:35], 0, v[130:131]
	s_mov_b32 m0, s54
	ds_read_b128 v[202:205], v171 offset:16384
	ds_read_b128 v[206:209], v171 offset:17408
	ds_read_b128 v[210:213], v171 offset:18432
	ds_read_b128 v[214:217], v171 offset:19456
	ds_read_b128 v[218:221], v171 offset:20480
	ds_read_b128 v[222:225], v171 offset:21504
	ds_read_b128 v[226:229], v171 offset:22528
	ds_read_b128 v[230:233], v171 offset:23552
	global_load_lds_dwordx4 v[186:187], off
	s_add_i32 m0, s54, 0x2000
	s_add_u32 s54, s34, 0x20000
	v_lshl_add_u64 v[234:235], s[34:35], 0, v[134:135]
	s_addc_u32 s55, s35, 0
	s_add_i32 s58, s48, s26
	global_load_lds_dwordx4 v[234:235], off
	v_lshl_add_u64 v[236:237], s[54:55], 0, v[130:131]
	s_mov_b32 m0, s58
	v_lshl_add_u64 v[238:239], s[36:37], 0, v[132:133]
	global_load_lds_dwordx4 v[236:237], off
	v_lshl_add_u64 v[236:237], s[54:55], 0, v[134:135]
	s_add_i32 m0, s58, 0x2000
	s_nop 0
	global_load_lds_dwordx4 v[236:237], off
	v_lshl_add_u64 v[236:237], s[36:37], 0, v[128:129]
	s_mov_b32 m0, s15
	s_nop 0
	global_load_lds_dwordx4 v[236:237], off
	s_mov_b32 m0, s27
	s_nop 0
	global_load_lds_dwordx4 v[238:239], off
	s_waitcnt vmcnt(8)
	s_waitcnt lgkmcnt(0)
	s_barrier
	v_mfma_f32_16x16x32_bf16 v[60:63], v[154:157], v[202:205], v[60:63]
	v_mfma_f32_16x16x32_bf16 v[56:59], v[174:177], v[202:205], v[56:59]
	v_mfma_f32_16x16x32_bf16 v[44:47], v[154:157], v[210:213], v[44:47]
	v_mfma_f32_16x16x32_bf16 v[40:43], v[174:177], v[210:213], v[40:43]
	v_mfma_f32_16x16x32_bf16 v[28:31], v[154:157], v[218:221], v[28:31]
	v_mfma_f32_16x16x32_bf16 v[24:27], v[174:177], v[218:221], v[24:27]
	v_mfma_f32_16x16x32_bf16 v[12:15], v[154:157], v[226:229], v[12:15]
	v_mfma_f32_16x16x32_bf16 v[8:11], v[174:177], v[226:229], v[8:11]
	v_mfma_f32_16x16x32_bf16 v[60:63], v[158:161], v[206:209], v[60:63]
	v_mfma_f32_16x16x32_bf16 v[56:59], v[178:181], v[206:209], v[56:59]
	v_mfma_f32_16x16x32_bf16 v[44:47], v[158:161], v[214:217], v[44:47]
	v_mfma_f32_16x16x32_bf16 v[40:43], v[178:181], v[214:217], v[40:43]
	v_mfma_f32_16x16x32_bf16 v[28:31], v[158:161], v[222:225], v[28:31]
	v_mfma_f32_16x16x32_bf16 v[24:27], v[178:181], v[222:225], v[24:27]
	v_mfma_f32_16x16x32_bf16 v[12:15], v[158:161], v[230:233], v[12:15]
	v_mfma_f32_16x16x32_bf16 v[8:11], v[178:181], v[230:233], v[8:11]
	v_mfma_f32_16x16x32_bf16 v[52:55], v[182:185], v[202:205], v[52:55]
	v_mfma_f32_16x16x32_bf16 v[48:51], v[194:197], v[202:205], v[48:51]
	v_mfma_f32_16x16x32_bf16 v[36:39], v[182:185], v[210:213], v[36:39]
	v_mfma_f32_16x16x32_bf16 v[32:35], v[194:197], v[210:213], v[32:35]
	v_mfma_f32_16x16x32_bf16 v[20:23], v[182:185], v[218:221], v[20:23]
	v_mfma_f32_16x16x32_bf16 v[16:19], v[194:197], v[218:221], v[16:19]
	v_mfma_f32_16x16x32_bf16 v[4:7], v[182:185], v[226:229], v[4:7]
	v_mfma_f32_16x16x32_bf16 v[0:3], v[194:197], v[226:229], v[0:3]
	v_mfma_f32_16x16x32_bf16 v[52:55], v[190:193], v[206:209], v[52:55]
	v_mfma_f32_16x16x32_bf16 v[48:51], v[198:201], v[206:209], v[48:51]
	v_mfma_f32_16x16x32_bf16 v[36:39], v[190:193], v[214:217], v[36:39]
	v_mfma_f32_16x16x32_bf16 v[32:35], v[198:201], v[214:217], v[32:35]
	v_mfma_f32_16x16x32_bf16 v[20:23], v[190:193], v[222:225], v[20:23]
	v_mfma_f32_16x16x32_bf16 v[16:19], v[198:201], v[222:225], v[16:19]
	v_mfma_f32_16x16x32_bf16 v[4:7], v[190:193], v[230:233], v[4:7]
	v_mfma_f32_16x16x32_bf16 v[0:3], v[198:201], v[230:233], v[0:3]
	s_barrier
	s_add_i32 s54, 0, 0x18000
	v_add_u32_e32 v138, s54, v169
	s_add_i32 s55, 0, 0x1c000
	ds_read_b128 v[154:157], v138
	ds_read_b128 v[158:161], v138 offset:1024
	ds_read_b128 v[174:177], v138 offset:2048
	ds_read_b128 v[178:181], v138 offset:3072
	v_add_u32_e32 v138, s55, v169
	ds_read_b128 v[182:185], v138
	ds_read_b128 v[190:193], v138 offset:1024
	ds_read_b128 v[194:197], v138 offset:2048
	ds_read_b128 v[198:201], v138 offset:3072
	s_add_u32 s36, s36, 0x20000
	s_addc_u32 s37, s37, 0
	s_mov_b32 m0, s38
	v_lshl_add_u64 v[240:241], s[36:37], 0, v[128:129]
	ds_read_b128 v[202:205], v171 offset:32768
	ds_read_b128 v[206:209], v171 offset:33792
	ds_read_b128 v[210:213], v171 offset:34816
	ds_read_b128 v[214:217], v171 offset:35840
	ds_read_b128 v[218:221], v171 offset:36864
	ds_read_b128 v[222:225], v171 offset:37888
	ds_read_b128 v[226:229], v171 offset:38912
	ds_read_b128 v[230:233], v171 offset:39936
	global_load_lds_dwordx4 v[240:241], off
	v_lshl_add_u64 v[240:241], s[36:37], 0, v[132:133]
	s_mov_b32 m0, s39
	s_nop 0
	global_load_lds_dwordx4 v[240:241], off
	s_waitcnt vmcnt(8)
	s_waitcnt lgkmcnt(0)
	s_barrier
	v_mfma_f32_16x16x32_bf16 v[124:127], v[154:157], v[202:205], v[124:127]
	v_mfma_f32_16x16x32_bf16 v[120:123], v[174:177], v[202:205], v[120:123]
	v_mfma_f32_16x16x32_bf16 v[108:111], v[154:157], v[210:213], v[108:111]
	v_mfma_f32_16x16x32_bf16 v[104:107], v[174:177], v[210:213], v[104:107]
	v_mfma_f32_16x16x32_bf16 v[92:95], v[154:157], v[218:221], v[92:95]
	v_mfma_f32_16x16x32_bf16 v[88:91], v[174:177], v[218:221], v[88:91]
	v_mfma_f32_16x16x32_bf16 v[76:79], v[154:157], v[226:229], v[76:79]
	v_mfma_f32_16x16x32_bf16 v[72:75], v[174:177], v[226:229], v[72:75]
	v_mfma_f32_16x16x32_bf16 v[124:127], v[158:161], v[206:209], v[124:127]
	v_mfma_f32_16x16x32_bf16 v[120:123], v[178:181], v[206:209], v[120:123]
	v_mfma_f32_16x16x32_bf16 v[108:111], v[158:161], v[214:217], v[108:111]
	v_mfma_f32_16x16x32_bf16 v[104:107], v[178:181], v[214:217], v[104:107]
	v_mfma_f32_16x16x32_bf16 v[92:95], v[158:161], v[222:225], v[92:95]
	v_mfma_f32_16x16x32_bf16 v[88:91], v[178:181], v[222:225], v[88:91]
	v_mfma_f32_16x16x32_bf16 v[76:79], v[158:161], v[230:233], v[76:79]
	v_mfma_f32_16x16x32_bf16 v[72:75], v[178:181], v[230:233], v[72:75]
	v_mfma_f32_16x16x32_bf16 v[116:119], v[182:185], v[202:205], v[116:119]
	v_mfma_f32_16x16x32_bf16 v[112:115], v[194:197], v[202:205], v[112:115]
	v_mfma_f32_16x16x32_bf16 v[100:103], v[182:185], v[210:213], v[100:103]
	v_mfma_f32_16x16x32_bf16 v[96:99], v[194:197], v[210:213], v[96:99]
	v_mfma_f32_16x16x32_bf16 v[84:87], v[182:185], v[218:221], v[84:87]
	v_mfma_f32_16x16x32_bf16 v[80:83], v[194:197], v[218:221], v[80:83]
	v_mfma_f32_16x16x32_bf16 v[68:71], v[182:185], v[226:229], v[68:71]
	v_mfma_f32_16x16x32_bf16 v[64:67], v[194:197], v[226:229], v[64:67]
	v_mfma_f32_16x16x32_bf16 v[116:119], v[190:193], v[206:209], v[116:119]
	v_mfma_f32_16x16x32_bf16 v[112:115], v[198:201], v[206:209], v[112:115]
	v_mfma_f32_16x16x32_bf16 v[100:103], v[190:193], v[214:217], v[100:103]
	v_mfma_f32_16x16x32_bf16 v[96:99], v[198:201], v[214:217], v[96:99]
	v_mfma_f32_16x16x32_bf16 v[84:87], v[190:193], v[222:225], v[84:87]
	v_mfma_f32_16x16x32_bf16 v[80:83], v[198:201], v[222:225], v[80:83]
	v_mfma_f32_16x16x32_bf16 v[68:71], v[190:193], v[230:233], v[68:71]
	v_mfma_f32_16x16x32_bf16 v[64:67], v[198:201], v[230:233], v[64:67]
	s_barrier
	s_add_i32 s36, s54, s26
	v_lshl_add_u64 v[186:187], v[186:187], 0, s[20:21]
	s_mov_b32 m0, s36
	ds_read_b128 v[202:205], v171 offset:49152
	ds_read_b128 v[206:209], v171 offset:50176
	ds_read_b128 v[210:213], v171 offset:51200
	ds_read_b128 v[214:217], v171 offset:52224
	ds_read_b128 v[218:221], v171 offset:53248
	ds_read_b128 v[222:225], v171 offset:54272
	ds_read_b128 v[226:229], v171 offset:55296
	ds_read_b128 v[230:233], v171 offset:56320
	global_load_lds_dwordx4 v[186:187], off
	s_add_i32 m0, s36, 0x2000
	s_add_u32 s34, s34, 0x20080
	v_lshl_add_u64 v[186:187], v[234:235], 0, s[20:21]
	s_addc_u32 s35, s35, 0
	s_add_i32 s36, s55, s26
	global_load_lds_dwordx4 v[186:187], off
	v_lshl_add_u64 v[186:187], s[34:35], 0, v[130:131]
	s_mov_b32 m0, s36
	s_nop 0
	global_load_lds_dwordx4 v[186:187], off
	v_lshl_add_u64 v[186:187], s[34:35], 0, v[134:135]
	s_add_i32 m0, s36, 0x2000
	s_nop 0
	global_load_lds_dwordx4 v[186:187], off
	v_lshl_add_u64 v[186:187], v[236:237], 0, s[20:21]
	s_mov_b32 m0, s41
	s_nop 0
	global_load_lds_dwordx4 v[186:187], off
	v_lshl_add_u64 v[186:187], v[238:239], 0, s[20:21]
	s_mov_b32 m0, s42
	s_nop 0
	global_load_lds_dwordx4 v[186:187], off
	s_waitcnt vmcnt(8)
	s_waitcnt lgkmcnt(0)
	s_barrier
	v_mfma_f32_16x16x32_bf16 v[60:63], v[154:157], v[202:205], v[60:63]
	v_mfma_f32_16x16x32_bf16 v[56:59], v[174:177], v[202:205], v[56:59]
	v_mfma_f32_16x16x32_bf16 v[44:47], v[154:157], v[210:213], v[44:47]
	v_mfma_f32_16x16x32_bf16 v[40:43], v[174:177], v[210:213], v[40:43]
	v_mfma_f32_16x16x32_bf16 v[28:31], v[154:157], v[218:221], v[28:31]
	v_mfma_f32_16x16x32_bf16 v[24:27], v[174:177], v[218:221], v[24:27]
	v_mfma_f32_16x16x32_bf16 v[12:15], v[154:157], v[226:229], v[12:15]
	v_mfma_f32_16x16x32_bf16 v[8:11], v[174:177], v[226:229], v[8:11]
	v_mfma_f32_16x16x32_bf16 v[60:63], v[158:161], v[206:209], v[60:63]
	v_mfma_f32_16x16x32_bf16 v[56:59], v[178:181], v[206:209], v[56:59]
	v_mfma_f32_16x16x32_bf16 v[44:47], v[158:161], v[214:217], v[44:47]
	v_mfma_f32_16x16x32_bf16 v[40:43], v[178:181], v[214:217], v[40:43]
	v_mfma_f32_16x16x32_bf16 v[28:31], v[158:161], v[222:225], v[28:31]
	v_mfma_f32_16x16x32_bf16 v[24:27], v[178:181], v[222:225], v[24:27]
	v_mfma_f32_16x16x32_bf16 v[12:15], v[158:161], v[230:233], v[12:15]
	v_mfma_f32_16x16x32_bf16 v[8:11], v[178:181], v[230:233], v[8:11]
	v_mfma_f32_16x16x32_bf16 v[52:55], v[182:185], v[202:205], v[52:55]
	v_mfma_f32_16x16x32_bf16 v[48:51], v[194:197], v[202:205], v[48:51]
	v_mfma_f32_16x16x32_bf16 v[36:39], v[182:185], v[210:213], v[36:39]
	v_mfma_f32_16x16x32_bf16 v[32:35], v[194:197], v[210:213], v[32:35]
	v_mfma_f32_16x16x32_bf16 v[20:23], v[182:185], v[218:221], v[20:23]
	v_mfma_f32_16x16x32_bf16 v[16:19], v[194:197], v[218:221], v[16:19]
	v_mfma_f32_16x16x32_bf16 v[4:7], v[182:185], v[226:229], v[4:7]
	v_mfma_f32_16x16x32_bf16 v[0:3], v[194:197], v[226:229], v[0:3]
	v_mfma_f32_16x16x32_bf16 v[52:55], v[190:193], v[206:209], v[52:55]
	v_mfma_f32_16x16x32_bf16 v[48:51], v[198:201], v[206:209], v[48:51]
	v_mfma_f32_16x16x32_bf16 v[36:39], v[190:193], v[214:217], v[36:39]
	v_mfma_f32_16x16x32_bf16 v[32:35], v[198:201], v[214:217], v[32:35]
	v_mfma_f32_16x16x32_bf16 v[20:23], v[190:193], v[222:225], v[20:23]
	v_mfma_f32_16x16x32_bf16 v[16:19], v[198:201], v[222:225], v[16:19]
	v_mfma_f32_16x16x32_bf16 v[4:7], v[190:193], v[230:233], v[4:7]
	v_mfma_f32_16x16x32_bf16 v[0:3], v[198:201], v[230:233], v[0:3]
	s_barrier
	s_add_i32 s53, s53, 2
	s_add_u32 s10, s10, 0x100
	s_addc_u32 s11, s11, 0
	s_add_u32 s51, s51, 0x100
	s_addc_u32 s52, s52, 0
	s_cmp_gt_u32 s53, 5
	s_cbranch_scc0 .LBB0_947
	s_and_b64 vcc, exec, s[22:23]
	s_cbranch_vccz .LBB0_950
	s_barrier

.LBB0_1037:
	ds_read_b128 v[148:151], v160
	ds_read_b128 v[152:155], v160 offset:1024
	ds_read_b128 v[166:169], v160 offset:2048
	ds_read_b128 v[170:173], v160 offset:3072
	ds_read_b128 v[174:177], v161
	ds_read_b128 v[178:181], v161 offset:1024
	ds_read_b128 v[182:185], v161 offset:2048
	ds_read_b128 v[190:193], v161 offset:3072
	s_add_u32 s34, s10, 0xfffe0080
	s_addc_u32 s35, s11, -1
	s_cmp_eq_u32 s51, 4
	s_cselect_b32 s37, s5, s35
	s_cselect_b32 s36, s12, s34
	s_cselect_b32 s35, s23, s50
	s_cselect_b32 s34, s27, s49
	v_lshl_add_u64 v[156:157], s[10:11], 0, v[140:141]
	s_add_i32 m0, s9, 0xc000
	ds_read_b128 v[194:197], v162
	ds_read_b128 v[198:201], v162 offset:1024
	ds_read_b128 v[202:205], v162 offset:2048
	ds_read_b128 v[206:209], v162 offset:3072
	ds_read_b128 v[210:213], v162 offset:4096
	ds_read_b128 v[214:217], v162 offset:5120
	ds_read_b128 v[218:221], v162 offset:6144
	ds_read_b128 v[222:225], v162 offset:7168
	global_load_lds_dwordx4 v[156:157], off
	v_lshl_add_u64 v[156:157], s[10:11], 0, v[142:143]
	s_add_i32 m0, s9, 0xe000
	s_nop 0
	global_load_lds_dwordx4 v[156:157], off
	s_waitcnt vmcnt(8)
	s_waitcnt lgkmcnt(0)
	s_barrier
	v_mfma_f32_16x16x32_bf16 v[124:127], v[148:151], v[194:197], v[124:127]
	v_mfma_f32_16x16x32_bf16 v[120:123], v[166:169], v[194:197], v[120:123]
	v_mfma_f32_16x16x32_bf16 v[108:111], v[148:151], v[202:205], v[108:111]
	v_mfma_f32_16x16x32_bf16 v[104:107], v[166:169], v[202:205], v[104:107]
	v_mfma_f32_16x16x32_bf16 v[92:95], v[148:151], v[210:213], v[92:95]
	v_mfma_f32_16x16x32_bf16 v[88:91], v[166:169], v[210:213], v[88:91]
	v_mfma_f32_16x16x32_bf16 v[76:79], v[148:151], v[218:221], v[76:79]
	v_mfma_f32_16x16x32_bf16 v[72:75], v[166:169], v[218:221], v[72:75]
	v_mfma_f32_16x16x32_bf16 v[124:127], v[152:155], v[198:201], v[124:127]
	v_mfma_f32_16x16x32_bf16 v[120:123], v[170:173], v[198:201], v[120:123]
	v_mfma_f32_16x16x32_bf16 v[108:111], v[152:155], v[206:209], v[108:111]
	v_mfma_f32_16x16x32_bf16 v[104:107], v[170:173], v[206:209], v[104:107]
	v_mfma_f32_16x16x32_bf16 v[92:95], v[152:155], v[214:217], v[92:95]
	v_mfma_f32_16x16x32_bf16 v[88:91], v[170:173], v[214:217], v[88:91]
	v_mfma_f32_16x16x32_bf16 v[76:79], v[152:155], v[222:225], v[76:79]
	v_mfma_f32_16x16x32_bf16 v[72:75], v[170:173], v[222:225], v[72:75]
	v_mfma_f32_16x16x32_bf16 v[116:119], v[174:177], v[194:197], v[116:119]
	v_mfma_f32_16x16x32_bf16 v[112:115], v[182:185], v[194:197], v[112:115]
	v_mfma_f32_16x16x32_bf16 v[100:103], v[174:177], v[202:205], v[100:103]
	v_mfma_f32_16x16x32_bf16 v[96:99], v[182:185], v[202:205], v[96:99]
	v_mfma_f32_16x16x32_bf16 v[84:87], v[174:177], v[210:213], v[84:87]
	v_mfma_f32_16x16x32_bf16 v[80:83], v[182:185], v[210:213], v[80:83]
	v_mfma_f32_16x16x32_bf16 v[68:71], v[174:177], v[218:221], v[68:71]
	v_mfma_f32_16x16x32_bf16 v[64:67], v[182:185], v[218:221], v[64:67]
	v_mfma_f32_16x16x32_bf16 v[116:119], v[178:181], v[198:201], v[116:119]
	v_mfma_f32_16x16x32_bf16 v[112:115], v[190:193], v[198:201], v[112:115]
	v_mfma_f32_16x16x32_bf16 v[100:103], v[178:181], v[206:209], v[100:103]
	v_mfma_f32_16x16x32_bf16 v[96:99], v[190:193], v[206:209], v[96:99]
	v_mfma_f32_16x16x32_bf16 v[84:87], v[178:181], v[214:217], v[84:87]
	v_mfma_f32_16x16x32_bf16 v[80:83], v[190:193], v[214:217], v[80:83]
	v_mfma_f32_16x16x32_bf16 v[68:71], v[178:181], v[222:225], v[68:71]
	v_mfma_f32_16x16x32_bf16 v[64:67], v[190:193], v[222:225], v[64:67]
	s_barrier
	s_add_i32 s52, s45, s24
	v_lshl_add_u64 v[156:157], s[34:35], 0, v[130:131]
	s_mov_b32 m0, s52
	ds_read_b128 v[194:197], v162 offset:16384
	ds_read_b128 v[198:201], v162 offset:17408
	ds_read_b128 v[202:205], v162 offset:18432
	ds_read_b128 v[206:209], v162 offset:19456
	ds_read_b128 v[210:213], v162 offset:20480
	ds_read_b128 v[214:217], v162 offset:21504
	ds_read_b128 v[218:221], v162 offset:22528
	ds_read_b128 v[222:225], v162 offset:23552
	global_load_lds_dwordx4 v[156:157], off
	s_add_i32 m0, s52, 0x2000
	s_add_u32 s52, s34, 0x20000
	v_lshl_add_u64 v[186:187], s[34:35], 0, v[134:135]
	s_addc_u32 s53, s35, 0
	s_add_i32 s54, s46, s24
	global_load_lds_dwordx4 v[186:187], off
	v_lshl_add_u64 v[226:227], s[52:53], 0, v[130:131]
	s_mov_b32 m0, s54
	v_lshl_add_u64 v[228:229], s[36:37], 0, v[132:133]
	global_load_lds_dwordx4 v[226:227], off
	v_lshl_add_u64 v[226:227], s[52:53], 0, v[134:135]
	s_add_i32 m0, s54, 0x2000
	s_nop 0
	global_load_lds_dwordx4 v[226:227], off
	v_lshl_add_u64 v[226:227], s[36:37], 0, v[128:129]
	s_mov_b32 m0, s9
	s_nop 0
	global_load_lds_dwordx4 v[226:227], off
	s_mov_b32 m0, s25
	s_nop 0
	global_load_lds_dwordx4 v[228:229], off
	s_waitcnt vmcnt(8)
	s_waitcnt lgkmcnt(0)
	s_barrier
	v_mfma_f32_16x16x32_bf16 v[60:63], v[148:151], v[194:197], v[60:63]
	v_mfma_f32_16x16x32_bf16 v[56:59], v[166:169], v[194:197], v[56:59]
	v_mfma_f32_16x16x32_bf16 v[44:47], v[148:151], v[202:205], v[44:47]
	v_mfma_f32_16x16x32_bf16 v[40:43], v[166:169], v[202:205], v[40:43]
	v_mfma_f32_16x16x32_bf16 v[28:31], v[148:151], v[210:213], v[28:31]
	v_mfma_f32_16x16x32_bf16 v[24:27], v[166:169], v[210:213], v[24:27]
	v_mfma_f32_16x16x32_bf16 v[12:15], v[148:151], v[218:221], v[12:15]
	v_mfma_f32_16x16x32_bf16 v[8:11], v[166:169], v[218:221], v[8:11]
	v_mfma_f32_16x16x32_bf16 v[60:63], v[152:155], v[198:201], v[60:63]
	v_mfma_f32_16x16x32_bf16 v[56:59], v[170:173], v[198:201], v[56:59]
	v_mfma_f32_16x16x32_bf16 v[44:47], v[152:155], v[206:209], v[44:47]
	v_mfma_f32_16x16x32_bf16 v[40:43], v[170:173], v[206:209], v[40:43]
	v_mfma_f32_16x16x32_bf16 v[28:31], v[152:155], v[214:217], v[28:31]
	v_mfma_f32_16x16x32_bf16 v[24:27], v[170:173], v[214:217], v[24:27]
	v_mfma_f32_16x16x32_bf16 v[12:15], v[152:155], v[222:225], v[12:15]
	v_mfma_f32_16x16x32_bf16 v[8:11], v[170:173], v[222:225], v[8:11]
	v_mfma_f32_16x16x32_bf16 v[52:55], v[174:177], v[194:197], v[52:55]
	v_mfma_f32_16x16x32_bf16 v[48:51], v[182:185], v[194:197], v[48:51]
	v_mfma_f32_16x16x32_bf16 v[36:39], v[174:177], v[202:205], v[36:39]
	v_mfma_f32_16x16x32_bf16 v[32:35], v[182:185], v[202:205], v[32:35]
	v_mfma_f32_16x16x32_bf16 v[20:23], v[174:177], v[210:213], v[20:23]
	v_mfma_f32_16x16x32_bf16 v[16:19], v[182:185], v[210:213], v[16:19]
	v_mfma_f32_16x16x32_bf16 v[4:7], v[174:177], v[218:221], v[4:7]
	v_mfma_f32_16x16x32_bf16 v[0:3], v[182:185], v[218:221], v[0:3]
	v_mfma_f32_16x16x32_bf16 v[52:55], v[178:181], v[198:201], v[52:55]
	v_mfma_f32_16x16x32_bf16 v[48:51], v[190:193], v[198:201], v[48:51]
	v_mfma_f32_16x16x32_bf16 v[36:39], v[178:181], v[206:209], v[36:39]
	v_mfma_f32_16x16x32_bf16 v[32:35], v[190:193], v[206:209], v[32:35]
	v_mfma_f32_16x16x32_bf16 v[20:23], v[178:181], v[214:217], v[20:23]
	v_mfma_f32_16x16x32_bf16 v[16:19], v[190:193], v[214:217], v[16:19]
	v_mfma_f32_16x16x32_bf16 v[4:7], v[178:181], v[222:225], v[4:7]
	v_mfma_f32_16x16x32_bf16 v[0:3], v[190:193], v[222:225], v[0:3]
	s_barrier
	s_add_i32 s52, 0, 0x18000
	v_add_u32_e32 v165, s52, v159
	s_add_i32 s53, 0, 0x1c000
	ds_read_b128 v[148:151], v165
	ds_read_b128 v[152:155], v165 offset:1024
	ds_read_b128 v[166:169], v165 offset:2048
	ds_read_b128 v[170:173], v165 offset:3072
	v_add_u32_e32 v165, s53, v159
	ds_read_b128 v[174:177], v165
	ds_read_b128 v[178:181], v165 offset:1024
	ds_read_b128 v[182:185], v165 offset:2048
	ds_read_b128 v[190:193], v165 offset:3072
	s_add_u32 s36, s36, 0x20000
	s_addc_u32 s37, s37, 0
	s_mov_b32 m0, s38
	v_lshl_add_u64 v[230:231], s[36:37], 0, v[128:129]
	ds_read_b128 v[194:197], v162 offset:32768
	ds_read_b128 v[198:201], v162 offset:33792
	ds_read_b128 v[202:205], v162 offset:34816
	ds_read_b128 v[206:209], v162 offset:35840
	ds_read_b128 v[210:213], v162 offset:36864
	ds_read_b128 v[214:217], v162 offset:37888
	ds_read_b128 v[218:221], v162 offset:38912
	ds_read_b128 v[222:225], v162 offset:39936
	global_load_lds_dwordx4 v[230:231], off
	v_lshl_add_u64 v[230:231], s[36:37], 0, v[132:133]
	s_mov_b32 m0, s39
	s_nop 0
	global_load_lds_dwordx4 v[230:231], off
	s_waitcnt vmcnt(8)
	s_waitcnt lgkmcnt(0)
	s_barrier
	v_mfma_f32_16x16x32_bf16 v[124:127], v[148:151], v[194:197], v[124:127]
	v_mfma_f32_16x16x32_bf16 v[120:123], v[166:169], v[194:197], v[120:123]
	v_mfma_f32_16x16x32_bf16 v[108:111], v[148:151], v[202:205], v[108:111]
	v_mfma_f32_16x16x32_bf16 v[104:107], v[166:169], v[202:205], v[104:107]
	v_mfma_f32_16x16x32_bf16 v[92:95], v[148:151], v[210:213], v[92:95]
	v_mfma_f32_16x16x32_bf16 v[88:91], v[166:169], v[210:213], v[88:91]
	v_mfma_f32_16x16x32_bf16 v[76:79], v[148:151], v[218:221], v[76:79]
	v_mfma_f32_16x16x32_bf16 v[72:75], v[166:169], v[218:221], v[72:75]
	v_mfma_f32_16x16x32_bf16 v[124:127], v[152:155], v[198:201], v[124:127]
	v_mfma_f32_16x16x32_bf16 v[120:123], v[170:173], v[198:201], v[120:123]
	v_mfma_f32_16x16x32_bf16 v[108:111], v[152:155], v[206:209], v[108:111]
	v_mfma_f32_16x16x32_bf16 v[104:107], v[170:173], v[206:209], v[104:107]
	v_mfma_f32_16x16x32_bf16 v[92:95], v[152:155], v[214:217], v[92:95]
	v_mfma_f32_16x16x32_bf16 v[88:91], v[170:173], v[214:217], v[88:91]
	v_mfma_f32_16x16x32_bf16 v[76:79], v[152:155], v[222:225], v[76:79]
	v_mfma_f32_16x16x32_bf16 v[72:75], v[170:173], v[222:225], v[72:75]
	v_mfma_f32_16x16x32_bf16 v[116:119], v[174:177], v[194:197], v[116:119]
	v_mfma_f32_16x16x32_bf16 v[112:115], v[182:185], v[194:197], v[112:115]
	v_mfma_f32_16x16x32_bf16 v[100:103], v[174:177], v[202:205], v[100:103]
	v_mfma_f32_16x16x32_bf16 v[96:99], v[182:185], v[202:205], v[96:99]
	v_mfma_f32_16x16x32_bf16 v[84:87], v[174:177], v[210:213], v[84:87]
	v_mfma_f32_16x16x32_bf16 v[80:83], v[182:185], v[210:213], v[80:83]
	v_mfma_f32_16x16x32_bf16 v[68:71], v[174:177], v[218:221], v[68:71]
	v_mfma_f32_16x16x32_bf16 v[64:67], v[182:185], v[218:221], v[64:67]
	v_mfma_f32_16x16x32_bf16 v[116:119], v[178:181], v[198:201], v[116:119]
	v_mfma_f32_16x16x32_bf16 v[112:115], v[190:193], v[198:201], v[112:115]
	v_mfma_f32_16x16x32_bf16 v[100:103], v[178:181], v[206:209], v[100:103]
	v_mfma_f32_16x16x32_bf16 v[96:99], v[190:193], v[206:209], v[96:99]
	v_mfma_f32_16x16x32_bf16 v[84:87], v[178:181], v[214:217], v[84:87]
	v_mfma_f32_16x16x32_bf16 v[80:83], v[190:193], v[214:217], v[80:83]
	v_mfma_f32_16x16x32_bf16 v[68:71], v[178:181], v[222:225], v[68:71]
	v_mfma_f32_16x16x32_bf16 v[64:67], v[190:193], v[222:225], v[64:67]
	s_barrier
	s_add_i32 s36, s52, s24
	v_lshl_add_u64 v[156:157], v[156:157], 0, s[16:17]
	s_mov_b32 m0, s36
	ds_read_b128 v[194:197], v162 offset:49152
	ds_read_b128 v[198:201], v162 offset:50176
	ds_read_b128 v[202:205], v162 offset:51200
	ds_read_b128 v[206:209], v162 offset:52224
	ds_read_b128 v[210:213], v162 offset:53248
	ds_read_b128 v[214:217], v162 offset:54272
	ds_read_b128 v[218:221], v162 offset:55296
	ds_read_b128 v[222:225], v162 offset:56320
	global_load_lds_dwordx4 v[156:157], off
	s_add_i32 m0, s36, 0x2000
	s_add_u32 s34, s34, 0x20080
	v_lshl_add_u64 v[156:157], v[186:187], 0, s[16:17]
	s_addc_u32 s35, s35, 0
	s_add_i32 s36, s53, s24
	global_load_lds_dwordx4 v[156:157], off
	v_lshl_add_u64 v[156:157], s[34:35], 0, v[130:131]
	s_mov_b32 m0, s36
	s_nop 0
	global_load_lds_dwordx4 v[156:157], off
	v_lshl_add_u64 v[156:157], s[34:35], 0, v[134:135]
	s_add_i32 m0, s36, 0x2000
	s_nop 0
	global_load_lds_dwordx4 v[156:157], off
	v_lshl_add_u64 v[156:157], v[226:227], 0, s[16:17]
	s_mov_b32 m0, s41
	s_nop 0
	global_load_lds_dwordx4 v[156:157], off
	v_lshl_add_u64 v[156:157], v[228:229], 0, s[16:17]
	s_mov_b32 m0, s42
	s_nop 0
	global_load_lds_dwordx4 v[156:157], off
	s_waitcnt vmcnt(8)
	s_waitcnt lgkmcnt(0)
	s_barrier
	v_mfma_f32_16x16x32_bf16 v[60:63], v[148:151], v[194:197], v[60:63]
	v_mfma_f32_16x16x32_bf16 v[56:59], v[166:169], v[194:197], v[56:59]
	v_mfma_f32_16x16x32_bf16 v[44:47], v[148:151], v[202:205], v[44:47]
	v_mfma_f32_16x16x32_bf16 v[40:43], v[166:169], v[202:205], v[40:43]
	v_mfma_f32_16x16x32_bf16 v[28:31], v[148:151], v[210:213], v[28:31]
	v_mfma_f32_16x16x32_bf16 v[24:27], v[166:169], v[210:213], v[24:27]
	v_mfma_f32_16x16x32_bf16 v[12:15], v[148:151], v[218:221], v[12:15]
	v_mfma_f32_16x16x32_bf16 v[8:11], v[166:169], v[218:221], v[8:11]
	v_mfma_f32_16x16x32_bf16 v[60:63], v[152:155], v[198:201], v[60:63]
	v_mfma_f32_16x16x32_bf16 v[56:59], v[170:173], v[198:201], v[56:59]
	v_mfma_f32_16x16x32_bf16 v[44:47], v[152:155], v[206:209], v[44:47]
	v_mfma_f32_16x16x32_bf16 v[40:43], v[170:173], v[206:209], v[40:43]
	v_mfma_f32_16x16x32_bf16 v[28:31], v[152:155], v[214:217], v[28:31]
	v_mfma_f32_16x16x32_bf16 v[24:27], v[170:173], v[214:217], v[24:27]
	v_mfma_f32_16x16x32_bf16 v[12:15], v[152:155], v[222:225], v[12:15]
	v_mfma_f32_16x16x32_bf16 v[8:11], v[170:173], v[222:225], v[8:11]
	v_mfma_f32_16x16x32_bf16 v[52:55], v[174:177], v[194:197], v[52:55]
	v_mfma_f32_16x16x32_bf16 v[48:51], v[182:185], v[194:197], v[48:51]
	v_mfma_f32_16x16x32_bf16 v[36:39], v[174:177], v[202:205], v[36:39]
	v_mfma_f32_16x16x32_bf16 v[32:35], v[182:185], v[202:205], v[32:35]
	v_mfma_f32_16x16x32_bf16 v[20:23], v[174:177], v[210:213], v[20:23]
	v_mfma_f32_16x16x32_bf16 v[16:19], v[182:185], v[210:213], v[16:19]
	v_mfma_f32_16x16x32_bf16 v[4:7], v[174:177], v[218:221], v[4:7]
	v_mfma_f32_16x16x32_bf16 v[0:3], v[182:185], v[218:221], v[0:3]
	v_mfma_f32_16x16x32_bf16 v[52:55], v[178:181], v[198:201], v[52:55]
	v_mfma_f32_16x16x32_bf16 v[48:51], v[190:193], v[198:201], v[48:51]
	v_mfma_f32_16x16x32_bf16 v[36:39], v[178:181], v[206:209], v[36:39]
	v_mfma_f32_16x16x32_bf16 v[32:35], v[190:193], v[206:209], v[32:35]
	v_mfma_f32_16x16x32_bf16 v[20:23], v[178:181], v[214:217], v[20:23]
	v_mfma_f32_16x16x32_bf16 v[16:19], v[190:193], v[214:217], v[16:19]
	v_mfma_f32_16x16x32_bf16 v[4:7], v[178:181], v[222:225], v[4:7]
	v_mfma_f32_16x16x32_bf16 v[0:3], v[190:193], v[222:225], v[0:3]
	s_barrier
	s_add_i32 s51, s51, 2
	s_add_u32 s10, s10, 0x100
	s_addc_u32 s11, s11, 0
	s_add_u32 s49, s49, 0x100
	s_addc_u32 s50, s50, 0
	s_cmp_gt_u32 s51, 5
	s_cbranch_scc0 .LBB0_1037
	s_and_b64 vcc, exec, s[18:19]
	s_cbranch_vccz .LBB0_1040
	s_barrier

.LBB0_1452:
	ds_read_b128 v[128:131], v177
	ds_read_b128 v[132:135], v177 offset:1024
	ds_read_b128 v[136:139], v177 offset:2048
	ds_read_b128 v[140:143], v177 offset:3072
	ds_read_b128 v[160:163], v178
	ds_read_b128 v[164:167], v178 offset:1024
	ds_read_b128 v[168:171], v178 offset:2048
	ds_read_b128 v[182:185], v178 offset:3072
	s_add_u32 s28, s26, 0xfff80080
	s_addc_u32 s29, s27, -1
	s_cmp_eq_u32 s50, 28
	s_cselect_b32 s31, s15, s29
	s_cselect_b32 s30, s23, s28
	s_cselect_b32 s29, s17, s49
	s_cselect_b32 s28, s25, s48
	v_lshl_add_u64 v[172:173], s[26:27], 0, v[152:153]
	s_add_i32 m0, s34, 0xc000
	ds_read_b128 v[190:193], v179
	ds_read_b128 v[194:197], v179 offset:1024
	ds_read_b128 v[198:201], v179 offset:2048
	ds_read_b128 v[202:205], v179 offset:3072
	ds_read_b128 v[206:209], v179 offset:4096
	ds_read_b128 v[210:213], v179 offset:5120
	ds_read_b128 v[214:217], v179 offset:6144
	ds_read_b128 v[218:221], v179 offset:7168
	global_load_lds_dwordx4 v[172:173], off
	v_lshl_add_u64 v[172:173], s[26:27], 0, v[154:155]
	s_add_i32 m0, s34, 0xe000
	s_nop 0
	global_load_lds_dwordx4 v[172:173], off
	s_waitcnt vmcnt(8)
	s_waitcnt lgkmcnt(0)
	s_barrier
	v_mfma_f32_16x16x32_bf16 v[124:127], v[128:131], v[190:193], v[124:127]
	v_mfma_f32_16x16x32_bf16 v[120:123], v[136:139], v[190:193], v[120:123]
	v_mfma_f32_16x16x32_bf16 v[108:111], v[128:131], v[198:201], v[108:111]
	v_mfma_f32_16x16x32_bf16 v[104:107], v[136:139], v[198:201], v[104:107]
	v_mfma_f32_16x16x32_bf16 v[92:95], v[128:131], v[206:209], v[92:95]
	v_mfma_f32_16x16x32_bf16 v[88:91], v[136:139], v[206:209], v[88:91]
	v_mfma_f32_16x16x32_bf16 v[76:79], v[128:131], v[214:217], v[76:79]
	v_mfma_f32_16x16x32_bf16 v[72:75], v[136:139], v[214:217], v[72:75]
	v_mfma_f32_16x16x32_bf16 v[124:127], v[132:135], v[194:197], v[124:127]
	v_mfma_f32_16x16x32_bf16 v[120:123], v[140:143], v[194:197], v[120:123]
	v_mfma_f32_16x16x32_bf16 v[108:111], v[132:135], v[202:205], v[108:111]
	v_mfma_f32_16x16x32_bf16 v[104:107], v[140:143], v[202:205], v[104:107]
	v_mfma_f32_16x16x32_bf16 v[92:95], v[132:135], v[210:213], v[92:95]
	v_mfma_f32_16x16x32_bf16 v[88:91], v[140:143], v[210:213], v[88:91]
	v_mfma_f32_16x16x32_bf16 v[76:79], v[132:135], v[218:221], v[76:79]
	v_mfma_f32_16x16x32_bf16 v[72:75], v[140:143], v[218:221], v[72:75]
	v_mfma_f32_16x16x32_bf16 v[116:119], v[160:163], v[190:193], v[116:119]
	v_mfma_f32_16x16x32_bf16 v[112:115], v[168:171], v[190:193], v[112:115]
	v_mfma_f32_16x16x32_bf16 v[100:103], v[160:163], v[198:201], v[100:103]
	v_mfma_f32_16x16x32_bf16 v[96:99], v[168:171], v[198:201], v[96:99]
	v_mfma_f32_16x16x32_bf16 v[84:87], v[160:163], v[206:209], v[84:87]
	v_mfma_f32_16x16x32_bf16 v[80:83], v[168:171], v[206:209], v[80:83]
	v_mfma_f32_16x16x32_bf16 v[68:71], v[160:163], v[214:217], v[68:71]
	v_mfma_f32_16x16x32_bf16 v[64:67], v[168:171], v[214:217], v[64:67]
	v_mfma_f32_16x16x32_bf16 v[116:119], v[164:167], v[194:197], v[116:119]
	v_mfma_f32_16x16x32_bf16 v[112:115], v[182:185], v[194:197], v[112:115]
	v_mfma_f32_16x16x32_bf16 v[100:103], v[164:167], v[202:205], v[100:103]
	v_mfma_f32_16x16x32_bf16 v[96:99], v[182:185], v[202:205], v[96:99]
	v_mfma_f32_16x16x32_bf16 v[84:87], v[164:167], v[210:213], v[84:87]
	v_mfma_f32_16x16x32_bf16 v[80:83], v[182:185], v[210:213], v[80:83]
	v_mfma_f32_16x16x32_bf16 v[68:71], v[164:167], v[218:221], v[68:71]
	v_mfma_f32_16x16x32_bf16 v[64:67], v[182:185], v[218:221], v[64:67]
	s_barrier
	s_add_i32 s51, s45, s33
	v_lshl_add_u64 v[172:173], s[28:29], 0, v[146:147]
	s_mov_b32 m0, s51
	ds_read_b128 v[190:193], v179 offset:16384
	ds_read_b128 v[194:197], v179 offset:17408
	ds_read_b128 v[198:201], v179 offset:18432
	ds_read_b128 v[202:205], v179 offset:19456
	ds_read_b128 v[206:209], v179 offset:20480
	ds_read_b128 v[210:213], v179 offset:21504
	ds_read_b128 v[214:217], v179 offset:22528
	ds_read_b128 v[218:221], v179 offset:23552
	global_load_lds_dwordx4 v[172:173], off
	s_add_i32 m0, s51, 0x2000
	s_add_u32 s52, s28, 0x80000
	v_lshl_add_u64 v[186:187], s[28:29], 0, v[150:151]
	s_addc_u32 s53, s29, 0
	s_add_i32 s51, s46, s33
	global_load_lds_dwordx4 v[186:187], off
	v_lshl_add_u64 v[222:223], s[52:53], 0, v[146:147]
	s_mov_b32 m0, s51
	v_lshl_add_u64 v[224:225], s[30:31], 0, v[148:149]
	global_load_lds_dwordx4 v[222:223], off
	v_lshl_add_u64 v[222:223], s[52:53], 0, v[150:151]
	s_add_i32 m0, s51, 0x2000
	s_nop 0
	global_load_lds_dwordx4 v[222:223], off
	v_lshl_add_u64 v[222:223], s[30:31], 0, v[144:145]
	s_mov_b32 m0, s34
	s_nop 0
	global_load_lds_dwordx4 v[222:223], off
	s_mov_b32 m0, s35
	s_nop 0
	global_load_lds_dwordx4 v[224:225], off
	s_waitcnt vmcnt(8)
	s_waitcnt lgkmcnt(0)
	s_barrier
	v_mfma_f32_16x16x32_bf16 v[60:63], v[128:131], v[190:193], v[60:63]
	v_mfma_f32_16x16x32_bf16 v[56:59], v[136:139], v[190:193], v[56:59]
	v_mfma_f32_16x16x32_bf16 v[44:47], v[128:131], v[198:201], v[44:47]
	v_mfma_f32_16x16x32_bf16 v[40:43], v[136:139], v[198:201], v[40:43]
	v_mfma_f32_16x16x32_bf16 v[28:31], v[128:131], v[206:209], v[28:31]
	v_mfma_f32_16x16x32_bf16 v[24:27], v[136:139], v[206:209], v[24:27]
	v_mfma_f32_16x16x32_bf16 v[12:15], v[128:131], v[214:217], v[12:15]
	v_mfma_f32_16x16x32_bf16 v[8:11], v[136:139], v[214:217], v[8:11]
	v_mfma_f32_16x16x32_bf16 v[60:63], v[132:135], v[194:197], v[60:63]
	v_mfma_f32_16x16x32_bf16 v[56:59], v[140:143], v[194:197], v[56:59]
	v_mfma_f32_16x16x32_bf16 v[44:47], v[132:135], v[202:205], v[44:47]
	v_mfma_f32_16x16x32_bf16 v[40:43], v[140:143], v[202:205], v[40:43]
	v_mfma_f32_16x16x32_bf16 v[28:31], v[132:135], v[210:213], v[28:31]
	v_mfma_f32_16x16x32_bf16 v[24:27], v[140:143], v[210:213], v[24:27]
	v_mfma_f32_16x16x32_bf16 v[12:15], v[132:135], v[218:221], v[12:15]
	v_mfma_f32_16x16x32_bf16 v[8:11], v[140:143], v[218:221], v[8:11]
	v_mfma_f32_16x16x32_bf16 v[52:55], v[160:163], v[190:193], v[52:55]
	v_mfma_f32_16x16x32_bf16 v[48:51], v[168:171], v[190:193], v[48:51]
	v_mfma_f32_16x16x32_bf16 v[36:39], v[160:163], v[198:201], v[36:39]
	v_mfma_f32_16x16x32_bf16 v[32:35], v[168:171], v[198:201], v[32:35]
	v_mfma_f32_16x16x32_bf16 v[20:23], v[160:163], v[206:209], v[20:23]
	v_mfma_f32_16x16x32_bf16 v[16:19], v[168:171], v[206:209], v[16:19]
	v_mfma_f32_16x16x32_bf16 v[4:7], v[160:163], v[214:217], v[4:7]
	v_mfma_f32_16x16x32_bf16 v[0:3], v[168:171], v[214:217], v[0:3]
	v_mfma_f32_16x16x32_bf16 v[52:55], v[164:167], v[194:197], v[52:55]
	v_mfma_f32_16x16x32_bf16 v[48:51], v[182:185], v[194:197], v[48:51]
	v_mfma_f32_16x16x32_bf16 v[36:39], v[164:167], v[202:205], v[36:39]
	v_mfma_f32_16x16x32_bf16 v[32:35], v[182:185], v[202:205], v[32:35]
	v_mfma_f32_16x16x32_bf16 v[20:23], v[164:167], v[210:213], v[20:23]
	v_mfma_f32_16x16x32_bf16 v[16:19], v[182:185], v[210:213], v[16:19]
	v_mfma_f32_16x16x32_bf16 v[4:7], v[164:167], v[218:221], v[4:7]
	v_mfma_f32_16x16x32_bf16 v[0:3], v[182:185], v[218:221], v[0:3]
	s_barrier
	s_add_i32 s51, 0, 0x18000
	s_add_i32 s52, 0, 0x1c000
	v_add_u32_e32 v140, s51, v175
	v_add_u32_e32 v181, s52, v175
	ds_read_b128 v[128:131], v140
	ds_read_b128 v[132:135], v140 offset:1024
	ds_read_b128 v[136:139], v140 offset:2048
	ds_read_b128 v[140:143], v140 offset:3072
	ds_read_b128 v[160:163], v181
	ds_read_b128 v[164:167], v181 offset:1024
	ds_read_b128 v[168:171], v181 offset:2048
	ds_read_b128 v[182:185], v181 offset:3072
	s_add_u32 s30, s30, 0x80000
	s_addc_u32 s31, s31, 0
	s_mov_b32 m0, s36
	v_lshl_add_u64 v[226:227], s[30:31], 0, v[144:145]
	ds_read_b128 v[190:193], v179 offset:32768
	ds_read_b128 v[194:197], v179 offset:33792
	ds_read_b128 v[198:201], v179 offset:34816
	ds_read_b128 v[202:205], v179 offset:35840
	ds_read_b128 v[206:209], v179 offset:36864
	ds_read_b128 v[210:213], v179 offset:37888
	ds_read_b128 v[214:217], v179 offset:38912
	ds_read_b128 v[218:221], v179 offset:39936
	global_load_lds_dwordx4 v[226:227], off
	v_lshl_add_u64 v[226:227], s[30:31], 0, v[148:149]
	s_mov_b32 m0, s37
	s_nop 0
	global_load_lds_dwordx4 v[226:227], off
	s_waitcnt vmcnt(8)
	s_waitcnt lgkmcnt(0)
	s_barrier
	v_mfma_f32_16x16x32_bf16 v[124:127], v[128:131], v[190:193], v[124:127]
	v_mfma_f32_16x16x32_bf16 v[120:123], v[136:139], v[190:193], v[120:123]
	v_mfma_f32_16x16x32_bf16 v[108:111], v[128:131], v[198:201], v[108:111]
	v_mfma_f32_16x16x32_bf16 v[104:107], v[136:139], v[198:201], v[104:107]
	v_mfma_f32_16x16x32_bf16 v[92:95], v[128:131], v[206:209], v[92:95]
	v_mfma_f32_16x16x32_bf16 v[88:91], v[136:139], v[206:209], v[88:91]
	v_mfma_f32_16x16x32_bf16 v[76:79], v[128:131], v[214:217], v[76:79]
	v_mfma_f32_16x16x32_bf16 v[72:75], v[136:139], v[214:217], v[72:75]
	v_mfma_f32_16x16x32_bf16 v[124:127], v[132:135], v[194:197], v[124:127]
	v_mfma_f32_16x16x32_bf16 v[120:123], v[140:143], v[194:197], v[120:123]
	v_mfma_f32_16x16x32_bf16 v[108:111], v[132:135], v[202:205], v[108:111]
	v_mfma_f32_16x16x32_bf16 v[104:107], v[140:143], v[202:205], v[104:107]
	v_mfma_f32_16x16x32_bf16 v[92:95], v[132:135], v[210:213], v[92:95]
	v_mfma_f32_16x16x32_bf16 v[88:91], v[140:143], v[210:213], v[88:91]
	v_mfma_f32_16x16x32_bf16 v[76:79], v[132:135], v[218:221], v[76:79]
	v_mfma_f32_16x16x32_bf16 v[72:75], v[140:143], v[218:221], v[72:75]
	v_mfma_f32_16x16x32_bf16 v[116:119], v[160:163], v[190:193], v[116:119]
	v_mfma_f32_16x16x32_bf16 v[112:115], v[168:171], v[190:193], v[112:115]
	v_mfma_f32_16x16x32_bf16 v[100:103], v[160:163], v[198:201], v[100:103]
	v_mfma_f32_16x16x32_bf16 v[96:99], v[168:171], v[198:201], v[96:99]
	v_mfma_f32_16x16x32_bf16 v[84:87], v[160:163], v[206:209], v[84:87]
	v_mfma_f32_16x16x32_bf16 v[80:83], v[168:171], v[206:209], v[80:83]
	v_mfma_f32_16x16x32_bf16 v[68:71], v[160:163], v[214:217], v[68:71]
	v_mfma_f32_16x16x32_bf16 v[64:67], v[168:171], v[214:217], v[64:67]
	v_mfma_f32_16x16x32_bf16 v[116:119], v[164:167], v[194:197], v[116:119]
	v_mfma_f32_16x16x32_bf16 v[112:115], v[182:185], v[194:197], v[112:115]
	v_mfma_f32_16x16x32_bf16 v[100:103], v[164:167], v[202:205], v[100:103]
	v_mfma_f32_16x16x32_bf16 v[96:99], v[182:185], v[202:205], v[96:99]
	v_mfma_f32_16x16x32_bf16 v[84:87], v[164:167], v[210:213], v[84:87]
	v_mfma_f32_16x16x32_bf16 v[80:83], v[182:185], v[210:213], v[80:83]
	v_mfma_f32_16x16x32_bf16 v[68:71], v[164:167], v[218:221], v[68:71]
	v_mfma_f32_16x16x32_bf16 v[64:67], v[182:185], v[218:221], v[64:67]
	s_barrier
	s_add_i32 s30, s51, s33
	v_lshl_add_u64 v[172:173], v[172:173], 0, s[8:9]
	s_mov_b32 m0, s30
	ds_read_b128 v[190:193], v179 offset:49152
	ds_read_b128 v[194:197], v179 offset:50176
	ds_read_b128 v[198:201], v179 offset:51200
	ds_read_b128 v[202:205], v179 offset:52224
	ds_read_b128 v[206:209], v179 offset:53248
	ds_read_b128 v[210:213], v179 offset:54272
	ds_read_b128 v[214:217], v179 offset:55296
	ds_read_b128 v[218:221], v179 offset:56320
	global_load_lds_dwordx4 v[172:173], off
	s_add_i32 m0, s30, 0x2000
	s_add_u32 s28, s28, 0x80080
	v_lshl_add_u64 v[172:173], v[186:187], 0, s[8:9]
	s_addc_u32 s29, s29, 0
	s_add_i32 s30, s52, s33
	global_load_lds_dwordx4 v[172:173], off
	v_lshl_add_u64 v[172:173], s[28:29], 0, v[146:147]
	s_mov_b32 m0, s30
	s_nop 0
	global_load_lds_dwordx4 v[172:173], off
	v_lshl_add_u64 v[172:173], s[28:29], 0, v[150:151]
	s_add_i32 m0, s30, 0x2000
	s_nop 0
	global_load_lds_dwordx4 v[172:173], off
	v_lshl_add_u64 v[172:173], v[222:223], 0, s[8:9]
	s_mov_b32 m0, s41
	s_nop 0
	global_load_lds_dwordx4 v[172:173], off
	v_lshl_add_u64 v[172:173], v[224:225], 0, s[8:9]
	s_mov_b32 m0, s42
	s_nop 0
	global_load_lds_dwordx4 v[172:173], off
	s_waitcnt vmcnt(8)
	s_waitcnt lgkmcnt(0)
	s_barrier
	v_mfma_f32_16x16x32_bf16 v[60:63], v[128:131], v[190:193], v[60:63]
	v_mfma_f32_16x16x32_bf16 v[56:59], v[136:139], v[190:193], v[56:59]
	v_mfma_f32_16x16x32_bf16 v[44:47], v[128:131], v[198:201], v[44:47]
	v_mfma_f32_16x16x32_bf16 v[40:43], v[136:139], v[198:201], v[40:43]
	v_mfma_f32_16x16x32_bf16 v[28:31], v[128:131], v[206:209], v[28:31]
	v_mfma_f32_16x16x32_bf16 v[24:27], v[136:139], v[206:209], v[24:27]
	v_mfma_f32_16x16x32_bf16 v[12:15], v[128:131], v[214:217], v[12:15]
	v_mfma_f32_16x16x32_bf16 v[8:11], v[136:139], v[214:217], v[8:11]
	v_mfma_f32_16x16x32_bf16 v[60:63], v[132:135], v[194:197], v[60:63]
	v_mfma_f32_16x16x32_bf16 v[56:59], v[140:143], v[194:197], v[56:59]
	v_mfma_f32_16x16x32_bf16 v[44:47], v[132:135], v[202:205], v[44:47]
	v_mfma_f32_16x16x32_bf16 v[40:43], v[140:143], v[202:205], v[40:43]
	v_mfma_f32_16x16x32_bf16 v[28:31], v[132:135], v[210:213], v[28:31]
	v_mfma_f32_16x16x32_bf16 v[24:27], v[140:143], v[210:213], v[24:27]
	v_mfma_f32_16x16x32_bf16 v[12:15], v[132:135], v[218:221], v[12:15]
	v_mfma_f32_16x16x32_bf16 v[8:11], v[140:143], v[218:221], v[8:11]
	v_mfma_f32_16x16x32_bf16 v[52:55], v[160:163], v[190:193], v[52:55]
	v_mfma_f32_16x16x32_bf16 v[48:51], v[168:171], v[190:193], v[48:51]
	v_mfma_f32_16x16x32_bf16 v[36:39], v[160:163], v[198:201], v[36:39]
	v_mfma_f32_16x16x32_bf16 v[32:35], v[168:171], v[198:201], v[32:35]
	v_mfma_f32_16x16x32_bf16 v[20:23], v[160:163], v[206:209], v[20:23]
	v_mfma_f32_16x16x32_bf16 v[16:19], v[168:171], v[206:209], v[16:19]
	v_mfma_f32_16x16x32_bf16 v[4:7], v[160:163], v[214:217], v[4:7]
	v_mfma_f32_16x16x32_bf16 v[0:3], v[168:171], v[214:217], v[0:3]
	v_mfma_f32_16x16x32_bf16 v[52:55], v[164:167], v[194:197], v[52:55]
	v_mfma_f32_16x16x32_bf16 v[48:51], v[182:185], v[194:197], v[48:51]
	v_mfma_f32_16x16x32_bf16 v[36:39], v[164:167], v[202:205], v[36:39]
	v_mfma_f32_16x16x32_bf16 v[32:35], v[182:185], v[202:205], v[32:35]
	v_mfma_f32_16x16x32_bf16 v[20:23], v[164:167], v[210:213], v[20:23]
	v_mfma_f32_16x16x32_bf16 v[16:19], v[182:185], v[210:213], v[16:19]
	v_mfma_f32_16x16x32_bf16 v[4:7], v[164:167], v[218:221], v[4:7]
	v_mfma_f32_16x16x32_bf16 v[0:3], v[182:185], v[218:221], v[0:3]
	s_barrier
	s_add_i32 s50, s50, 2
	s_add_u32 s26, s26, 0x100
	s_addc_u32 s27, s27, 0
	s_add_u32 s48, s48, 0x100
	s_addc_u32 s49, s49, 0
	s_cmp_gt_u32 s50, 29
	s_cbranch_scc0 .LBB0_1452
	s_and_b64 vcc, exec, s[10:11]
	s_cbranch_vccz .LBB0_1455
	s_barrier

.LBB0_1539:
	ds_read_b128 v[156:159], v151
	ds_read_b128 v[160:163], v151 offset:1024
	ds_read_b128 v[164:167], v151 offset:2048
	ds_read_b128 v[168:171], v151 offset:3072
	ds_read_b128 v[172:175], v152
	ds_read_b128 v[176:179], v152 offset:1024
	ds_read_b128 v[180:183], v152 offset:2048
	ds_read_b128 v[184:187], v152 offset:3072
	s_add_u32 s22, s20, 0xfff80080
	s_addc_u32 s23, s21, -1
	s_cmp_eq_u32 s48, 28
	s_cselect_b32 s25, s11, s23
	s_cselect_b32 s24, s44, s22
	s_cselect_b32 s23, s13, s47
	s_cselect_b32 s22, s45, s46
	v_lshl_add_u64 v[146:147], s[20:21], 0, v[138:139]
	s_add_i32 m0, s19, 0xc000
	ds_read_b128 v[190:193], v153
	ds_read_b128 v[194:197], v153 offset:1024
	ds_read_b128 v[198:201], v153 offset:2048
	ds_read_b128 v[202:205], v153 offset:3072
	ds_read_b128 v[206:209], v153 offset:4096
	ds_read_b128 v[210:213], v153 offset:5120
	ds_read_b128 v[214:217], v153 offset:6144
	ds_read_b128 v[218:221], v153 offset:7168
	global_load_lds_dwordx4 v[146:147], off
	v_lshl_add_u64 v[146:147], s[20:21], 0, v[140:141]
	s_add_i32 m0, s19, 0xe000
	s_nop 0
	global_load_lds_dwordx4 v[146:147], off
	s_waitcnt vmcnt(8)
	s_waitcnt lgkmcnt(0)
	s_barrier
	v_mfma_f32_16x16x32_bf16 v[116:119], v[156:159], v[190:193], v[116:119]
	v_mfma_f32_16x16x32_bf16 v[112:115], v[164:167], v[190:193], v[112:115]
	v_mfma_f32_16x16x32_bf16 v[100:103], v[156:159], v[198:201], v[100:103]
	v_mfma_f32_16x16x32_bf16 v[96:99], v[164:167], v[198:201], v[96:99]
	v_mfma_f32_16x16x32_bf16 v[84:87], v[156:159], v[206:209], v[84:87]
	v_mfma_f32_16x16x32_bf16 v[80:83], v[164:167], v[206:209], v[80:83]
	v_mfma_f32_16x16x32_bf16 v[68:71], v[156:159], v[214:217], v[68:71]
	v_mfma_f32_16x16x32_bf16 v[64:67], v[164:167], v[214:217], v[64:67]
	v_mfma_f32_16x16x32_bf16 v[116:119], v[160:163], v[194:197], v[116:119]
	v_mfma_f32_16x16x32_bf16 v[112:115], v[168:171], v[194:197], v[112:115]
	v_mfma_f32_16x16x32_bf16 v[100:103], v[160:163], v[202:205], v[100:103]
	v_mfma_f32_16x16x32_bf16 v[96:99], v[168:171], v[202:205], v[96:99]
	v_mfma_f32_16x16x32_bf16 v[84:87], v[160:163], v[210:213], v[84:87]
	v_mfma_f32_16x16x32_bf16 v[80:83], v[168:171], v[210:213], v[80:83]
	v_mfma_f32_16x16x32_bf16 v[68:71], v[160:163], v[218:221], v[68:71]
	v_mfma_f32_16x16x32_bf16 v[64:67], v[168:171], v[218:221], v[64:67]
	v_mfma_f32_16x16x32_bf16 v[124:127], v[172:175], v[190:193], v[124:127]
	v_mfma_f32_16x16x32_bf16 v[120:123], v[180:183], v[190:193], v[120:123]
	v_mfma_f32_16x16x32_bf16 v[108:111], v[172:175], v[198:201], v[108:111]
	v_mfma_f32_16x16x32_bf16 v[104:107], v[180:183], v[198:201], v[104:107]
	v_mfma_f32_16x16x32_bf16 v[92:95], v[172:175], v[206:209], v[92:95]
	v_mfma_f32_16x16x32_bf16 v[88:91], v[180:183], v[206:209], v[88:91]
	v_mfma_f32_16x16x32_bf16 v[76:79], v[172:175], v[214:217], v[76:79]
	v_mfma_f32_16x16x32_bf16 v[72:75], v[180:183], v[214:217], v[72:75]
	v_mfma_f32_16x16x32_bf16 v[124:127], v[176:179], v[194:197], v[124:127]
	v_mfma_f32_16x16x32_bf16 v[120:123], v[184:187], v[194:197], v[120:123]
	v_mfma_f32_16x16x32_bf16 v[108:111], v[176:179], v[202:205], v[108:111]
	v_mfma_f32_16x16x32_bf16 v[104:107], v[184:187], v[202:205], v[104:107]
	v_mfma_f32_16x16x32_bf16 v[92:95], v[176:179], v[210:213], v[92:95]
	v_mfma_f32_16x16x32_bf16 v[88:91], v[184:187], v[210:213], v[88:91]
	v_mfma_f32_16x16x32_bf16 v[76:79], v[176:179], v[218:221], v[76:79]
	v_mfma_f32_16x16x32_bf16 v[72:75], v[184:187], v[218:221], v[72:75]
	s_barrier
	s_add_i32 s49, s40, s28
	v_lshl_add_u64 v[146:147], s[22:23], 0, v[132:133]
	s_mov_b32 m0, s49
	ds_read_b128 v[190:193], v153 offset:16384
	ds_read_b128 v[194:197], v153 offset:17408
	ds_read_b128 v[198:201], v153 offset:18432
	ds_read_b128 v[202:205], v153 offset:19456
	ds_read_b128 v[206:209], v153 offset:20480
	ds_read_b128 v[210:213], v153 offset:21504
	ds_read_b128 v[214:217], v153 offset:22528
	ds_read_b128 v[218:221], v153 offset:23552
	global_load_lds_dwordx4 v[146:147], off
	s_add_i32 m0, s49, 0x2000
	s_add_u32 s50, s22, 0x80000
	v_lshl_add_u64 v[222:223], s[22:23], 0, v[128:129]
	s_addc_u32 s51, s23, 0
	s_add_i32 s49, s41, s28
	global_load_lds_dwordx4 v[222:223], off
	v_lshl_add_u64 v[224:225], s[50:51], 0, v[132:133]
	s_mov_b32 m0, s49
	v_lshl_add_u64 v[226:227], s[24:25], 0, v[130:131]
	global_load_lds_dwordx4 v[224:225], off
	v_lshl_add_u64 v[224:225], s[50:51], 0, v[128:129]
	s_add_i32 m0, s49, 0x2000
	s_nop 0
	global_load_lds_dwordx4 v[224:225], off
	v_lshl_add_u64 v[224:225], s[24:25], 0, v[134:135]
	s_mov_b32 m0, s19
	s_nop 0
	global_load_lds_dwordx4 v[224:225], off
	s_mov_b32 m0, s30
	s_nop 0
	global_load_lds_dwordx4 v[226:227], off
	s_waitcnt vmcnt(8)
	s_waitcnt lgkmcnt(0)
	s_barrier
	v_mfma_f32_16x16x32_bf16 v[52:55], v[156:159], v[190:193], v[52:55]
	v_mfma_f32_16x16x32_bf16 v[48:51], v[164:167], v[190:193], v[48:51]
	v_mfma_f32_16x16x32_bf16 v[36:39], v[156:159], v[198:201], v[36:39]
	v_mfma_f32_16x16x32_bf16 v[32:35], v[164:167], v[198:201], v[32:35]
	v_mfma_f32_16x16x32_bf16 v[20:23], v[156:159], v[206:209], v[20:23]
	v_mfma_f32_16x16x32_bf16 v[16:19], v[164:167], v[206:209], v[16:19]
	v_mfma_f32_16x16x32_bf16 v[8:11], v[156:159], v[214:217], v[8:11]
	v_mfma_f32_16x16x32_bf16 v[0:3], v[164:167], v[214:217], v[0:3]
	v_mfma_f32_16x16x32_bf16 v[52:55], v[160:163], v[194:197], v[52:55]
	v_mfma_f32_16x16x32_bf16 v[48:51], v[168:171], v[194:197], v[48:51]
	v_mfma_f32_16x16x32_bf16 v[36:39], v[160:163], v[202:205], v[36:39]
	v_mfma_f32_16x16x32_bf16 v[32:35], v[168:171], v[202:205], v[32:35]
	v_mfma_f32_16x16x32_bf16 v[20:23], v[160:163], v[210:213], v[20:23]
	v_mfma_f32_16x16x32_bf16 v[16:19], v[168:171], v[210:213], v[16:19]
	v_mfma_f32_16x16x32_bf16 v[8:11], v[160:163], v[218:221], v[8:11]
	v_mfma_f32_16x16x32_bf16 v[0:3], v[168:171], v[218:221], v[0:3]
	v_mfma_f32_16x16x32_bf16 v[60:63], v[172:175], v[190:193], v[60:63]
	v_mfma_f32_16x16x32_bf16 v[56:59], v[180:183], v[190:193], v[56:59]
	v_mfma_f32_16x16x32_bf16 v[44:47], v[172:175], v[198:201], v[44:47]
	v_mfma_f32_16x16x32_bf16 v[40:43], v[180:183], v[198:201], v[40:43]
	v_mfma_f32_16x16x32_bf16 v[28:31], v[172:175], v[206:209], v[28:31]
	v_mfma_f32_16x16x32_bf16 v[24:27], v[180:183], v[206:209], v[24:27]
	v_mfma_f32_16x16x32_bf16 v[12:15], v[172:175], v[214:217], v[12:15]
	v_mfma_f32_16x16x32_bf16 v[4:7], v[180:183], v[214:217], v[4:7]
	v_mfma_f32_16x16x32_bf16 v[60:63], v[176:179], v[194:197], v[60:63]
	v_mfma_f32_16x16x32_bf16 v[56:59], v[184:187], v[194:197], v[56:59]
	v_mfma_f32_16x16x32_bf16 v[44:47], v[176:179], v[202:205], v[44:47]
	v_mfma_f32_16x16x32_bf16 v[40:43], v[184:187], v[202:205], v[40:43]
	v_mfma_f32_16x16x32_bf16 v[28:31], v[176:179], v[210:213], v[28:31]
	v_mfma_f32_16x16x32_bf16 v[24:27], v[184:187], v[210:213], v[24:27]
	v_mfma_f32_16x16x32_bf16 v[12:15], v[176:179], v[218:221], v[12:15]
	v_mfma_f32_16x16x32_bf16 v[4:7], v[184:187], v[218:221], v[4:7]
	s_barrier
	s_add_i32 s49, 0, 0x18000
	s_add_i32 s50, 0, 0x1c000
	v_add_u32_e32 v168, s49, v149
	v_add_u32_e32 v184, s50, v149
	ds_read_b128 v[156:159], v168
	ds_read_b128 v[160:163], v168 offset:1024
	ds_read_b128 v[164:167], v168 offset:2048
	ds_read_b128 v[168:171], v168 offset:3072
	ds_read_b128 v[172:175], v184
	ds_read_b128 v[176:179], v184 offset:1024
	ds_read_b128 v[180:183], v184 offset:2048
	ds_read_b128 v[184:187], v184 offset:3072
	s_add_u32 s24, s24, 0x80000
	s_addc_u32 s25, s25, 0
	s_mov_b32 m0, s31
	v_lshl_add_u64 v[228:229], s[24:25], 0, v[134:135]
	ds_read_b128 v[190:193], v153 offset:32768
	ds_read_b128 v[194:197], v153 offset:33792
	ds_read_b128 v[198:201], v153 offset:34816
	ds_read_b128 v[202:205], v153 offset:35840
	ds_read_b128 v[206:209], v153 offset:36864
	ds_read_b128 v[210:213], v153 offset:37888
	ds_read_b128 v[214:217], v153 offset:38912
	ds_read_b128 v[218:221], v153 offset:39936
	global_load_lds_dwordx4 v[228:229], off
	v_lshl_add_u64 v[228:229], s[24:25], 0, v[130:131]
	s_mov_b32 m0, s33
	s_nop 0
	global_load_lds_dwordx4 v[228:229], off
	s_waitcnt vmcnt(8)
	s_waitcnt lgkmcnt(0)
	s_barrier
	v_mfma_f32_16x16x32_bf16 v[116:119], v[156:159], v[190:193], v[116:119]
	v_mfma_f32_16x16x32_bf16 v[112:115], v[164:167], v[190:193], v[112:115]
	v_mfma_f32_16x16x32_bf16 v[100:103], v[156:159], v[198:201], v[100:103]
	v_mfma_f32_16x16x32_bf16 v[96:99], v[164:167], v[198:201], v[96:99]
	v_mfma_f32_16x16x32_bf16 v[84:87], v[156:159], v[206:209], v[84:87]
	v_mfma_f32_16x16x32_bf16 v[80:83], v[164:167], v[206:209], v[80:83]
	v_mfma_f32_16x16x32_bf16 v[68:71], v[156:159], v[214:217], v[68:71]
	v_mfma_f32_16x16x32_bf16 v[64:67], v[164:167], v[214:217], v[64:67]
	v_mfma_f32_16x16x32_bf16 v[116:119], v[160:163], v[194:197], v[116:119]
	v_mfma_f32_16x16x32_bf16 v[112:115], v[168:171], v[194:197], v[112:115]
	v_mfma_f32_16x16x32_bf16 v[100:103], v[160:163], v[202:205], v[100:103]
	v_mfma_f32_16x16x32_bf16 v[96:99], v[168:171], v[202:205], v[96:99]
	v_mfma_f32_16x16x32_bf16 v[84:87], v[160:163], v[210:213], v[84:87]
	v_mfma_f32_16x16x32_bf16 v[80:83], v[168:171], v[210:213], v[80:83]
	v_mfma_f32_16x16x32_bf16 v[68:71], v[160:163], v[218:221], v[68:71]
	v_mfma_f32_16x16x32_bf16 v[64:67], v[168:171], v[218:221], v[64:67]
	v_mfma_f32_16x16x32_bf16 v[124:127], v[172:175], v[190:193], v[124:127]
	v_mfma_f32_16x16x32_bf16 v[120:123], v[180:183], v[190:193], v[120:123]
	v_mfma_f32_16x16x32_bf16 v[108:111], v[172:175], v[198:201], v[108:111]
	v_mfma_f32_16x16x32_bf16 v[104:107], v[180:183], v[198:201], v[104:107]
	v_mfma_f32_16x16x32_bf16 v[92:95], v[172:175], v[206:209], v[92:95]
	v_mfma_f32_16x16x32_bf16 v[88:91], v[180:183], v[206:209], v[88:91]
	v_mfma_f32_16x16x32_bf16 v[76:79], v[172:175], v[214:217], v[76:79]
	v_mfma_f32_16x16x32_bf16 v[72:75], v[180:183], v[214:217], v[72:75]
	v_mfma_f32_16x16x32_bf16 v[124:127], v[176:179], v[194:197], v[124:127]
	v_mfma_f32_16x16x32_bf16 v[120:123], v[184:187], v[194:197], v[120:123]
	v_mfma_f32_16x16x32_bf16 v[108:111], v[176:179], v[202:205], v[108:111]
	v_mfma_f32_16x16x32_bf16 v[104:107], v[184:187], v[202:205], v[104:107]
	v_mfma_f32_16x16x32_bf16 v[92:95], v[176:179], v[210:213], v[92:95]
	v_mfma_f32_16x16x32_bf16 v[88:91], v[184:187], v[210:213], v[88:91]
	v_mfma_f32_16x16x32_bf16 v[76:79], v[176:179], v[218:221], v[76:79]
	v_mfma_f32_16x16x32_bf16 v[72:75], v[184:187], v[218:221], v[72:75]
	s_barrier
	s_add_i32 s24, s49, s28
	v_lshl_add_u64 v[146:147], v[146:147], 0, s[6:7]
	s_mov_b32 m0, s24
	ds_read_b128 v[190:193], v153 offset:49152
	ds_read_b128 v[194:197], v153 offset:50176
	ds_read_b128 v[198:201], v153 offset:51200
	ds_read_b128 v[202:205], v153 offset:52224
	ds_read_b128 v[206:209], v153 offset:53248
	ds_read_b128 v[210:213], v153 offset:54272
	ds_read_b128 v[214:217], v153 offset:55296
	ds_read_b128 v[218:221], v153 offset:56320
	global_load_lds_dwordx4 v[146:147], off
	s_add_i32 m0, s24, 0x2000
	s_add_u32 s22, s22, 0x80080
	v_lshl_add_u64 v[146:147], v[222:223], 0, s[6:7]
	s_addc_u32 s23, s23, 0
	s_add_i32 s24, s50, s28
	global_load_lds_dwordx4 v[146:147], off
	v_lshl_add_u64 v[146:147], s[22:23], 0, v[132:133]
	s_mov_b32 m0, s24
	s_nop 0
	global_load_lds_dwordx4 v[146:147], off
	v_lshl_add_u64 v[146:147], s[22:23], 0, v[128:129]
	s_add_i32 m0, s24, 0x2000
	s_nop 0
	global_load_lds_dwordx4 v[146:147], off
	v_lshl_add_u64 v[146:147], v[224:225], 0, s[6:7]
	s_mov_b32 m0, s36
	s_nop 0
	global_load_lds_dwordx4 v[146:147], off
	v_lshl_add_u64 v[146:147], v[226:227], 0, s[6:7]
	s_mov_b32 m0, s37
	s_nop 0
	global_load_lds_dwordx4 v[146:147], off
	s_waitcnt vmcnt(8)
	s_waitcnt lgkmcnt(0)
	s_barrier
	v_mfma_f32_16x16x32_bf16 v[52:55], v[156:159], v[190:193], v[52:55]
	v_mfma_f32_16x16x32_bf16 v[48:51], v[164:167], v[190:193], v[48:51]
	v_mfma_f32_16x16x32_bf16 v[36:39], v[156:159], v[198:201], v[36:39]
	v_mfma_f32_16x16x32_bf16 v[32:35], v[164:167], v[198:201], v[32:35]
	v_mfma_f32_16x16x32_bf16 v[20:23], v[156:159], v[206:209], v[20:23]
	v_mfma_f32_16x16x32_bf16 v[16:19], v[164:167], v[206:209], v[16:19]
	v_mfma_f32_16x16x32_bf16 v[8:11], v[156:159], v[214:217], v[8:11]
	v_mfma_f32_16x16x32_bf16 v[0:3], v[164:167], v[214:217], v[0:3]
	v_mfma_f32_16x16x32_bf16 v[52:55], v[160:163], v[194:197], v[52:55]
	v_mfma_f32_16x16x32_bf16 v[48:51], v[168:171], v[194:197], v[48:51]
	v_mfma_f32_16x16x32_bf16 v[36:39], v[160:163], v[202:205], v[36:39]
	v_mfma_f32_16x16x32_bf16 v[32:35], v[168:171], v[202:205], v[32:35]
	v_mfma_f32_16x16x32_bf16 v[20:23], v[160:163], v[210:213], v[20:23]
	v_mfma_f32_16x16x32_bf16 v[16:19], v[168:171], v[210:213], v[16:19]
	v_mfma_f32_16x16x32_bf16 v[8:11], v[160:163], v[218:221], v[8:11]
	v_mfma_f32_16x16x32_bf16 v[0:3], v[168:171], v[218:221], v[0:3]
	v_mfma_f32_16x16x32_bf16 v[60:63], v[172:175], v[190:193], v[60:63]
	v_mfma_f32_16x16x32_bf16 v[56:59], v[180:183], v[190:193], v[56:59]
	v_mfma_f32_16x16x32_bf16 v[44:47], v[172:175], v[198:201], v[44:47]
	v_mfma_f32_16x16x32_bf16 v[40:43], v[180:183], v[198:201], v[40:43]
	v_mfma_f32_16x16x32_bf16 v[28:31], v[172:175], v[206:209], v[28:31]
	v_mfma_f32_16x16x32_bf16 v[24:27], v[180:183], v[206:209], v[24:27]
	v_mfma_f32_16x16x32_bf16 v[12:15], v[172:175], v[214:217], v[12:15]
	v_mfma_f32_16x16x32_bf16 v[4:7], v[180:183], v[214:217], v[4:7]
	v_mfma_f32_16x16x32_bf16 v[60:63], v[176:179], v[194:197], v[60:63]
	v_mfma_f32_16x16x32_bf16 v[56:59], v[184:187], v[194:197], v[56:59]
	v_mfma_f32_16x16x32_bf16 v[44:47], v[176:179], v[202:205], v[44:47]
	v_mfma_f32_16x16x32_bf16 v[40:43], v[184:187], v[202:205], v[40:43]
	v_mfma_f32_16x16x32_bf16 v[28:31], v[176:179], v[210:213], v[28:31]
	v_mfma_f32_16x16x32_bf16 v[24:27], v[184:187], v[210:213], v[24:27]
	v_mfma_f32_16x16x32_bf16 v[12:15], v[176:179], v[218:221], v[12:15]
	v_mfma_f32_16x16x32_bf16 v[4:7], v[184:187], v[218:221], v[4:7]
	s_barrier
	s_add_i32 s48, s48, 2
	s_add_u32 s20, s20, 0x100
	s_addc_u32 s21, s21, 0
	s_add_u32 s46, s46, 0x100
	s_addc_u32 s47, s47, 0
	s_cmp_gt_u32 s48, 29
	s_cbranch_scc0 .LBB0_1539
	s_and_b64 vcc, exec, s[8:9]
	s_cbranch_vccz .LBB0_1542
	s_barrier

.LBB0_1624:
	ds_read_b128 v[128:131], v177
	ds_read_b128 v[132:135], v177 offset:1024
	ds_read_b128 v[136:139], v177 offset:2048
	ds_read_b128 v[140:143], v177 offset:3072
	ds_read_b128 v[160:163], v178
	ds_read_b128 v[164:167], v178 offset:1024
	ds_read_b128 v[168:171], v178 offset:2048
	ds_read_b128 v[182:185], v178 offset:3072
	s_add_u32 s20, s18, 0xffea0080
	s_addc_u32 s21, s19, -1
	s_cmpk_eq_i32 s48, 0x54
	s_cselect_b32 s23, s1, s21
	s_cselect_b32 s22, s0, s20
	s_cselect_b32 s21, s17, s47
	s_cselect_b32 s20, s16, s46
	v_lshl_add_u64 v[172:173], s[18:19], 0, v[152:153]
	s_add_i32 m0, s27, 0xc000
	ds_read_b128 v[190:193], v179
	ds_read_b128 v[194:197], v179 offset:1024
	ds_read_b128 v[198:201], v179 offset:2048
	ds_read_b128 v[202:205], v179 offset:3072
	ds_read_b128 v[206:209], v179 offset:4096
	ds_read_b128 v[210:213], v179 offset:5120
	ds_read_b128 v[214:217], v179 offset:6144
	ds_read_b128 v[218:221], v179 offset:7168
	global_load_lds_dwordx4 v[172:173], off
	v_lshl_add_u64 v[172:173], s[18:19], 0, v[154:155]
	s_add_i32 m0, s27, 0xe000
	s_nop 0
	global_load_lds_dwordx4 v[172:173], off
	s_waitcnt vmcnt(8)
	s_waitcnt lgkmcnt(0)
	s_barrier
	v_mfma_f32_16x16x32_bf16 v[124:127], v[128:131], v[190:193], v[124:127]
	v_mfma_f32_16x16x32_bf16 v[120:123], v[136:139], v[190:193], v[120:123]
	v_mfma_f32_16x16x32_bf16 v[108:111], v[128:131], v[198:201], v[108:111]
	v_mfma_f32_16x16x32_bf16 v[104:107], v[136:139], v[198:201], v[104:107]
	v_mfma_f32_16x16x32_bf16 v[92:95], v[128:131], v[206:209], v[92:95]
	v_mfma_f32_16x16x32_bf16 v[88:91], v[136:139], v[206:209], v[88:91]
	v_mfma_f32_16x16x32_bf16 v[76:79], v[128:131], v[214:217], v[76:79]
	v_mfma_f32_16x16x32_bf16 v[72:75], v[136:139], v[214:217], v[72:75]
	v_mfma_f32_16x16x32_bf16 v[124:127], v[132:135], v[194:197], v[124:127]
	v_mfma_f32_16x16x32_bf16 v[120:123], v[140:143], v[194:197], v[120:123]
	v_mfma_f32_16x16x32_bf16 v[108:111], v[132:135], v[202:205], v[108:111]
	v_mfma_f32_16x16x32_bf16 v[104:107], v[140:143], v[202:205], v[104:107]
	v_mfma_f32_16x16x32_bf16 v[92:95], v[132:135], v[210:213], v[92:95]
	v_mfma_f32_16x16x32_bf16 v[88:91], v[140:143], v[210:213], v[88:91]
	v_mfma_f32_16x16x32_bf16 v[76:79], v[132:135], v[218:221], v[76:79]
	v_mfma_f32_16x16x32_bf16 v[72:75], v[140:143], v[218:221], v[72:75]
	v_mfma_f32_16x16x32_bf16 v[116:119], v[160:163], v[190:193], v[116:119]
	v_mfma_f32_16x16x32_bf16 v[112:115], v[168:171], v[190:193], v[112:115]
	v_mfma_f32_16x16x32_bf16 v[100:103], v[160:163], v[198:201], v[100:103]
	v_mfma_f32_16x16x32_bf16 v[96:99], v[168:171], v[198:201], v[96:99]
	v_mfma_f32_16x16x32_bf16 v[84:87], v[160:163], v[206:209], v[84:87]
	v_mfma_f32_16x16x32_bf16 v[80:83], v[168:171], v[206:209], v[80:83]
	v_mfma_f32_16x16x32_bf16 v[68:71], v[160:163], v[214:217], v[68:71]
	v_mfma_f32_16x16x32_bf16 v[64:67], v[168:171], v[214:217], v[64:67]
	v_mfma_f32_16x16x32_bf16 v[116:119], v[164:167], v[194:197], v[116:119]
	v_mfma_f32_16x16x32_bf16 v[112:115], v[182:185], v[194:197], v[112:115]
	v_mfma_f32_16x16x32_bf16 v[100:103], v[164:167], v[202:205], v[100:103]
	v_mfma_f32_16x16x32_bf16 v[96:99], v[182:185], v[202:205], v[96:99]
	v_mfma_f32_16x16x32_bf16 v[84:87], v[164:167], v[210:213], v[84:87]
	v_mfma_f32_16x16x32_bf16 v[80:83], v[182:185], v[210:213], v[80:83]
	v_mfma_f32_16x16x32_bf16 v[68:71], v[164:167], v[218:221], v[68:71]
	v_mfma_f32_16x16x32_bf16 v[64:67], v[182:185], v[218:221], v[64:67]
	s_barrier
	s_add_i32 s49, s39, s26
	v_lshl_add_u64 v[172:173], s[20:21], 0, v[146:147]
	s_mov_b32 m0, s49
	ds_read_b128 v[190:193], v179 offset:16384
	ds_read_b128 v[194:197], v179 offset:17408
	ds_read_b128 v[198:201], v179 offset:18432
	ds_read_b128 v[202:205], v179 offset:19456
	ds_read_b128 v[206:209], v179 offset:20480
	ds_read_b128 v[210:213], v179 offset:21504
	ds_read_b128 v[214:217], v179 offset:22528
	ds_read_b128 v[218:221], v179 offset:23552
	global_load_lds_dwordx4 v[172:173], off
	s_add_i32 m0, s49, 0x2000
	s_add_u32 s50, s20, 0x160000
	v_lshl_add_u64 v[186:187], s[20:21], 0, v[150:151]
	s_addc_u32 s51, s21, 0
	s_add_i32 s49, s40, s26
	global_load_lds_dwordx4 v[186:187], off
	v_lshl_add_u64 v[222:223], s[50:51], 0, v[146:147]
	s_mov_b32 m0, s49
	v_lshl_add_u64 v[224:225], s[22:23], 0, v[148:149]
	global_load_lds_dwordx4 v[222:223], off
	v_lshl_add_u64 v[222:223], s[50:51], 0, v[150:151]
	s_add_i32 m0, s49, 0x2000
	s_nop 0
	global_load_lds_dwordx4 v[222:223], off
	v_lshl_add_u64 v[222:223], s[22:23], 0, v[144:145]
	s_mov_b32 m0, s27
	s_nop 0
	global_load_lds_dwordx4 v[222:223], off
	s_mov_b32 m0, s28
	s_nop 0
	global_load_lds_dwordx4 v[224:225], off
	s_waitcnt vmcnt(8)
	s_waitcnt lgkmcnt(0)
	s_barrier
	v_mfma_f32_16x16x32_bf16 v[60:63], v[128:131], v[190:193], v[60:63]
	v_mfma_f32_16x16x32_bf16 v[56:59], v[136:139], v[190:193], v[56:59]
	v_mfma_f32_16x16x32_bf16 v[44:47], v[128:131], v[198:201], v[44:47]
	v_mfma_f32_16x16x32_bf16 v[40:43], v[136:139], v[198:201], v[40:43]
	v_mfma_f32_16x16x32_bf16 v[28:31], v[128:131], v[206:209], v[28:31]
	v_mfma_f32_16x16x32_bf16 v[24:27], v[136:139], v[206:209], v[24:27]
	v_mfma_f32_16x16x32_bf16 v[12:15], v[128:131], v[214:217], v[12:15]
	v_mfma_f32_16x16x32_bf16 v[8:11], v[136:139], v[214:217], v[8:11]
	v_mfma_f32_16x16x32_bf16 v[60:63], v[132:135], v[194:197], v[60:63]
	v_mfma_f32_16x16x32_bf16 v[56:59], v[140:143], v[194:197], v[56:59]
	v_mfma_f32_16x16x32_bf16 v[44:47], v[132:135], v[202:205], v[44:47]
	v_mfma_f32_16x16x32_bf16 v[40:43], v[140:143], v[202:205], v[40:43]
	v_mfma_f32_16x16x32_bf16 v[28:31], v[132:135], v[210:213], v[28:31]
	v_mfma_f32_16x16x32_bf16 v[24:27], v[140:143], v[210:213], v[24:27]
	v_mfma_f32_16x16x32_bf16 v[12:15], v[132:135], v[218:221], v[12:15]
	v_mfma_f32_16x16x32_bf16 v[8:11], v[140:143], v[218:221], v[8:11]
	v_mfma_f32_16x16x32_bf16 v[52:55], v[160:163], v[190:193], v[52:55]
	v_mfma_f32_16x16x32_bf16 v[48:51], v[168:171], v[190:193], v[48:51]
	v_mfma_f32_16x16x32_bf16 v[36:39], v[160:163], v[198:201], v[36:39]
	v_mfma_f32_16x16x32_bf16 v[32:35], v[168:171], v[198:201], v[32:35]
	v_mfma_f32_16x16x32_bf16 v[20:23], v[160:163], v[206:209], v[20:23]
	v_mfma_f32_16x16x32_bf16 v[16:19], v[168:171], v[206:209], v[16:19]
	v_mfma_f32_16x16x32_bf16 v[4:7], v[160:163], v[214:217], v[4:7]
	v_mfma_f32_16x16x32_bf16 v[0:3], v[168:171], v[214:217], v[0:3]
	v_mfma_f32_16x16x32_bf16 v[52:55], v[164:167], v[194:197], v[52:55]
	v_mfma_f32_16x16x32_bf16 v[48:51], v[182:185], v[194:197], v[48:51]
	v_mfma_f32_16x16x32_bf16 v[36:39], v[164:167], v[202:205], v[36:39]
	v_mfma_f32_16x16x32_bf16 v[32:35], v[182:185], v[202:205], v[32:35]
	v_mfma_f32_16x16x32_bf16 v[20:23], v[164:167], v[210:213], v[20:23]
	v_mfma_f32_16x16x32_bf16 v[16:19], v[182:185], v[210:213], v[16:19]
	v_mfma_f32_16x16x32_bf16 v[4:7], v[164:167], v[218:221], v[4:7]
	v_mfma_f32_16x16x32_bf16 v[0:3], v[182:185], v[218:221], v[0:3]
	s_barrier
	s_add_i32 s49, 0, 0x18000
	s_add_i32 s50, 0, 0x1c000
	v_add_u32_e32 v140, s49, v175
	v_add_u32_e32 v181, s50, v175
	ds_read_b128 v[128:131], v140
	ds_read_b128 v[132:135], v140 offset:1024
	ds_read_b128 v[136:139], v140 offset:2048
	ds_read_b128 v[140:143], v140 offset:3072
	ds_read_b128 v[160:163], v181
	ds_read_b128 v[164:167], v181 offset:1024
	ds_read_b128 v[168:171], v181 offset:2048
	ds_read_b128 v[182:185], v181 offset:3072
	s_add_u32 s22, s22, 0x160000
	s_addc_u32 s23, s23, 0
	s_mov_b32 m0, s29
	v_lshl_add_u64 v[226:227], s[22:23], 0, v[144:145]
	ds_read_b128 v[190:193], v179 offset:32768
	ds_read_b128 v[194:197], v179 offset:33792
	ds_read_b128 v[198:201], v179 offset:34816
	ds_read_b128 v[202:205], v179 offset:35840
	ds_read_b128 v[206:209], v179 offset:36864
	ds_read_b128 v[210:213], v179 offset:37888
	ds_read_b128 v[214:217], v179 offset:38912
	ds_read_b128 v[218:221], v179 offset:39936
	global_load_lds_dwordx4 v[226:227], off
	v_lshl_add_u64 v[226:227], s[22:23], 0, v[148:149]
	s_mov_b32 m0, s30
	s_nop 0
	global_load_lds_dwordx4 v[226:227], off
	s_waitcnt vmcnt(8)
	s_waitcnt lgkmcnt(0)
	s_barrier
	v_mfma_f32_16x16x32_bf16 v[124:127], v[128:131], v[190:193], v[124:127]
	v_mfma_f32_16x16x32_bf16 v[120:123], v[136:139], v[190:193], v[120:123]
	v_mfma_f32_16x16x32_bf16 v[108:111], v[128:131], v[198:201], v[108:111]
	v_mfma_f32_16x16x32_bf16 v[104:107], v[136:139], v[198:201], v[104:107]
	v_mfma_f32_16x16x32_bf16 v[92:95], v[128:131], v[206:209], v[92:95]
	v_mfma_f32_16x16x32_bf16 v[88:91], v[136:139], v[206:209], v[88:91]
	v_mfma_f32_16x16x32_bf16 v[76:79], v[128:131], v[214:217], v[76:79]
	v_mfma_f32_16x16x32_bf16 v[72:75], v[136:139], v[214:217], v[72:75]
	v_mfma_f32_16x16x32_bf16 v[124:127], v[132:135], v[194:197], v[124:127]
	v_mfma_f32_16x16x32_bf16 v[120:123], v[140:143], v[194:197], v[120:123]
	v_mfma_f32_16x16x32_bf16 v[108:111], v[132:135], v[202:205], v[108:111]
	v_mfma_f32_16x16x32_bf16 v[104:107], v[140:143], v[202:205], v[104:107]
	v_mfma_f32_16x16x32_bf16 v[92:95], v[132:135], v[210:213], v[92:95]
	v_mfma_f32_16x16x32_bf16 v[88:91], v[140:143], v[210:213], v[88:91]
	v_mfma_f32_16x16x32_bf16 v[76:79], v[132:135], v[218:221], v[76:79]
	v_mfma_f32_16x16x32_bf16 v[72:75], v[140:143], v[218:221], v[72:75]
	v_mfma_f32_16x16x32_bf16 v[116:119], v[160:163], v[190:193], v[116:119]
	v_mfma_f32_16x16x32_bf16 v[112:115], v[168:171], v[190:193], v[112:115]
	v_mfma_f32_16x16x32_bf16 v[100:103], v[160:163], v[198:201], v[100:103]
	v_mfma_f32_16x16x32_bf16 v[96:99], v[168:171], v[198:201], v[96:99]
	v_mfma_f32_16x16x32_bf16 v[84:87], v[160:163], v[206:209], v[84:87]
	v_mfma_f32_16x16x32_bf16 v[80:83], v[168:171], v[206:209], v[80:83]
	v_mfma_f32_16x16x32_bf16 v[68:71], v[160:163], v[214:217], v[68:71]
	v_mfma_f32_16x16x32_bf16 v[64:67], v[168:171], v[214:217], v[64:67]
	v_mfma_f32_16x16x32_bf16 v[116:119], v[164:167], v[194:197], v[116:119]
	v_mfma_f32_16x16x32_bf16 v[112:115], v[182:185], v[194:197], v[112:115]
	v_mfma_f32_16x16x32_bf16 v[100:103], v[164:167], v[202:205], v[100:103]
	v_mfma_f32_16x16x32_bf16 v[96:99], v[182:185], v[202:205], v[96:99]
	v_mfma_f32_16x16x32_bf16 v[84:87], v[164:167], v[210:213], v[84:87]
	v_mfma_f32_16x16x32_bf16 v[80:83], v[182:185], v[210:213], v[80:83]
	v_mfma_f32_16x16x32_bf16 v[68:71], v[164:167], v[218:221], v[68:71]
	v_mfma_f32_16x16x32_bf16 v[64:67], v[182:185], v[218:221], v[64:67]
	s_barrier
	s_add_i32 s22, s49, s26
	v_lshl_add_u64 v[172:173], v[172:173], 0, s[10:11]
	s_mov_b32 m0, s22
	ds_read_b128 v[190:193], v179 offset:49152
	ds_read_b128 v[194:197], v179 offset:50176
	ds_read_b128 v[198:201], v179 offset:51200
	ds_read_b128 v[202:205], v179 offset:52224
	ds_read_b128 v[206:209], v179 offset:53248
	ds_read_b128 v[210:213], v179 offset:54272
	ds_read_b128 v[214:217], v179 offset:55296
	ds_read_b128 v[218:221], v179 offset:56320
	global_load_lds_dwordx4 v[172:173], off
	s_add_i32 m0, s22, 0x2000
	s_add_u32 s20, s20, 0x160080
	v_lshl_add_u64 v[172:173], v[186:187], 0, s[10:11]
	s_addc_u32 s21, s21, 0
	s_add_i32 s22, s50, s26
	global_load_lds_dwordx4 v[172:173], off
	v_lshl_add_u64 v[172:173], s[20:21], 0, v[146:147]
	s_mov_b32 m0, s22
	s_nop 0
	global_load_lds_dwordx4 v[172:173], off
	v_lshl_add_u64 v[172:173], s[20:21], 0, v[150:151]
	s_add_i32 m0, s22, 0x2000
	s_nop 0
	global_load_lds_dwordx4 v[172:173], off
	v_lshl_add_u64 v[172:173], v[222:223], 0, s[10:11]
	s_mov_b32 m0, s35
	s_nop 0
	global_load_lds_dwordx4 v[172:173], off
	v_lshl_add_u64 v[172:173], v[224:225], 0, s[10:11]
	s_mov_b32 m0, s36
	s_nop 0
	global_load_lds_dwordx4 v[172:173], off
	s_waitcnt vmcnt(8)
	s_waitcnt lgkmcnt(0)
	s_barrier
	v_mfma_f32_16x16x32_bf16 v[60:63], v[128:131], v[190:193], v[60:63]
	v_mfma_f32_16x16x32_bf16 v[56:59], v[136:139], v[190:193], v[56:59]
	v_mfma_f32_16x16x32_bf16 v[44:47], v[128:131], v[198:201], v[44:47]
	v_mfma_f32_16x16x32_bf16 v[40:43], v[136:139], v[198:201], v[40:43]
	v_mfma_f32_16x16x32_bf16 v[28:31], v[128:131], v[206:209], v[28:31]
	v_mfma_f32_16x16x32_bf16 v[24:27], v[136:139], v[206:209], v[24:27]
	v_mfma_f32_16x16x32_bf16 v[12:15], v[128:131], v[214:217], v[12:15]
	v_mfma_f32_16x16x32_bf16 v[8:11], v[136:139], v[214:217], v[8:11]
	v_mfma_f32_16x16x32_bf16 v[60:63], v[132:135], v[194:197], v[60:63]
	v_mfma_f32_16x16x32_bf16 v[56:59], v[140:143], v[194:197], v[56:59]
	v_mfma_f32_16x16x32_bf16 v[44:47], v[132:135], v[202:205], v[44:47]
	v_mfma_f32_16x16x32_bf16 v[40:43], v[140:143], v[202:205], v[40:43]
	v_mfma_f32_16x16x32_bf16 v[28:31], v[132:135], v[210:213], v[28:31]
	v_mfma_f32_16x16x32_bf16 v[24:27], v[140:143], v[210:213], v[24:27]
	v_mfma_f32_16x16x32_bf16 v[12:15], v[132:135], v[218:221], v[12:15]
	v_mfma_f32_16x16x32_bf16 v[8:11], v[140:143], v[218:221], v[8:11]
	v_mfma_f32_16x16x32_bf16 v[52:55], v[160:163], v[190:193], v[52:55]
	v_mfma_f32_16x16x32_bf16 v[48:51], v[168:171], v[190:193], v[48:51]
	v_mfma_f32_16x16x32_bf16 v[36:39], v[160:163], v[198:201], v[36:39]
	v_mfma_f32_16x16x32_bf16 v[32:35], v[168:171], v[198:201], v[32:35]
	v_mfma_f32_16x16x32_bf16 v[20:23], v[160:163], v[206:209], v[20:23]
	v_mfma_f32_16x16x32_bf16 v[16:19], v[168:171], v[206:209], v[16:19]
	v_mfma_f32_16x16x32_bf16 v[4:7], v[160:163], v[214:217], v[4:7]
	v_mfma_f32_16x16x32_bf16 v[0:3], v[168:171], v[214:217], v[0:3]
	v_mfma_f32_16x16x32_bf16 v[52:55], v[164:167], v[194:197], v[52:55]
	v_mfma_f32_16x16x32_bf16 v[48:51], v[182:185], v[194:197], v[48:51]
	v_mfma_f32_16x16x32_bf16 v[36:39], v[164:167], v[202:205], v[36:39]
	v_mfma_f32_16x16x32_bf16 v[32:35], v[182:185], v[202:205], v[32:35]
	v_mfma_f32_16x16x32_bf16 v[20:23], v[164:167], v[210:213], v[20:23]
	v_mfma_f32_16x16x32_bf16 v[16:19], v[182:185], v[210:213], v[16:19]
	v_mfma_f32_16x16x32_bf16 v[4:7], v[164:167], v[218:221], v[4:7]
	v_mfma_f32_16x16x32_bf16 v[0:3], v[182:185], v[218:221], v[0:3]
	s_barrier
	s_add_i32 s48, s48, 2
	s_add_u32 s18, s18, 0x100
	s_addc_u32 s19, s19, 0
	s_add_u32 s46, s46, 0x100
	s_addc_u32 s47, s47, 0
	s_cmpk_gt_u32 s48, 0x55
	s_cbranch_scc0 .LBB0_1624
	s_and_b64 vcc, exec, s[12:13]
	s_cbranch_vccz .LBB0_1627
	s_barrier
